# dense attention item: reference maximum kept while it grows by less than 8 (exact, shift-invariant) so accumulator rescale is skipped; packed f32 fma/add in softmax
# speedup vs baseline: 1.0056x; 1.0056x over previous
; #define LAS __attribute__((address_space(3)))
; DI int otid() { int t = threadIdx.x; asm volatile("" : "+v"(t)); return t; }
; template <int DK>
; DI void dense_attn_item(LAS unsigned char* lds, const bf16_t* Qb, int ldq, const bf16_t* Kb, int ldk, const bf16_t* Kpe, const bf16_t* Vt, int nkeys, float sl2, bf16_t* Ob) {
;     const int tid = otid(), lane = tid & 63, wid = tid >> 6, r16 = lane & 15, q4 = lane >> 4;
;     constexpr int KS = DK / 32, KCH = DK / 8, KROW = DK * 2 + 16, KTILE = 64 * KROW, VROW = 144, VTILE = 128 * VROW, NKL = (64 * KCH) / 512;
;     bf16x8 qf[2][KS];
; #pragma unroll
;     for (int qg = 0; qg < 2; ++qg)
; #pragma unroll
;         for (int ks = 0; ks < KS; ++ks) qf[qg][ks] = *(const bf16x8*)(Qb + (size_t)(wid * 32 + qg * 16 + r16) * ldq + ks * 32 + q4 * 8);
;     f32x4 oacc[2][8];
; #pragma unroll
;     for (int qg = 0; qg < 2; ++qg)
; #pragma unroll
;         for (int d = 0; d < 8; ++d) oacc[qg][d] = (f32x4){0.f, 0.f, 0.f, 0.f};
;     float mrun[2] = {-1e30f, -1e30f}, lsum[2] = {0.f, 0.f};
;     u32x4 kst[NKL], vst[2];
;     const int ntiles = nkeys >> 6;
;     ...
;     DA_LOAD(0); DA_STORE(0);
;     __syncthreads();
; DI void phase_dense_attn(const Params& p, int l, LAS unsigned char* lds) {
;     ...
;     for (int it = blockIdx.x; it < n_lat + n_ctx; it += gridDim.x) {
;         if (it < n_lat) {
;             const int qb = it & 7, h = (it >> 3) % 5, b = it / 40; const size_t rowb = (size_t)b * RB, row0 = rowb + CL + qb * 256;
;             dense_attn_item<192>(lds, (const bf16_t*)(ws + WS_QM) + row0 * 960 + h * 192, 960, (const bf16_t*)(ws + WS_KM) + rowb * 640 + h * 128, 640, (const bf16_t*)(ws + WS_KPE) + rowb * 64,
;                                  (const bf16_t*)(ws + WS_VTM) + ((size_t)b * 640 + h * 128) * RB, RB, 0.07216878364870322f * 1.4426950408889634f, ymix + row0 * DM + 768 + h * 128);
.LBB0_1146:
	s_mul_hi_u32 s71, s28, 0x66666667
	s_lshr_b32 s71, s71, 4
	s_lshr_b32 s73, s28, 3
	s_mul_i32 s62, s71, 5
	s_sub_u32 s73, s73, s62
	s_and_b32 s62, s28, 7
	s_lshl_b32 s62, s62, 8
	s_mul_i32 s75, s71, 0x900
	s_add_u32 s74, s75, s62
	s_addk_i32 s74, 0x100
	s_mul_i32 s62, s74, 0x780
	s_mul_i32 s63, s73, 0x180
	s_add_u32 s62, s62, s63
	s_add_u32 s62, s62, 0x1a3a0000
	s_add_u32 s10, s50, s62
	s_addc_u32 s11, s51, 0
	s_mul_i32 s62, s75, 0x500
	s_lshl_b32 s63, s73, 8
	s_add_u32 s62, s62, s63
	s_add_u32 s62, s62, 0x1b480000
	s_add_u32 s4, s50, s62
	s_addc_u32 s5, s51, 0
	s_mul_i32 s62, s75, 0x480
	s_add_u32 s62, s62, s63
	s_sub_u32 s76, 0x167ff00, s62
	s_mul_i32 s62, s71, 0x280
	s_lshl_b32 s63, s73, 7
	s_add_u32 s62, s62, s63
	s_mul_i32 s62, s62, 0x1200
	s_add_u32 s62, s62, 0x1bfc0000
	s_add_u32 s8, s50, s62
	s_addc_u32 s9, s51, 0
	s_lshl_b32 s62, s74, 12
	s_lshl_b32 s63, s73, 8
	s_add_u32 s62, s62, s63
	s_add_u32 s62, s62, 0x1d9a0600
	s_add_u32 s20, s50, s62
	s_addc_u32 s21, s51, 0
	s_mov_b32 s22, 0x3dd53b94
	v_mov_b32_e32 v254, s22
	s_mov_b32 s29, 0x41000000
	v_and_b32_e32 v192, 15, v202
	v_bfe_u32 v193, v202, 4, 2
	v_lshrrev_b32_e32 v194, 6, v202
	v_lshl_add_u32 v195, v194, 5, v192
	v_mul_u32_u24_e32 v196, 0x780, v195
	v_lshl_add_u32 v250, v193, 4, v196
	v_add_u32_e32 v251, 0x7800, v250
	global_load_dwordx4 v[0:3], v250, s[10:11] offset:0
	global_load_dwordx4 v[4:7], v250, s[10:11] offset:64
	global_load_dwordx4 v[8:11], v250, s[10:11] offset:128
	global_load_dwordx4 v[12:15], v250, s[10:11] offset:192
	global_load_dwordx4 v[16:19], v250, s[10:11] offset:256
	global_load_dwordx4 v[20:23], v250, s[10:11] offset:320
	global_load_dwordx4 v[24:27], v251, s[10:11] offset:0
	global_load_dwordx4 v[28:31], v251, s[10:11] offset:64
	global_load_dwordx4 v[32:35], v251, s[10:11] offset:128
	global_load_dwordx4 v[36:39], v251, s[10:11] offset:192
	global_load_dwordx4 v[40:43], v251, s[10:11] offset:256
	global_load_dwordx4 v[44:47], v251, s[10:11] offset:320
	s_mov_b32 s62, 0xaaaaaab
	v_mov_b32_e32 v197, v202
	v_mul_hi_u32 v198, v197, s62
	v_mul_u32_u24_e32 v195, 24, v198
	v_sub_u32_e32 v199, v197, v195
	v_mul_u32_u24_e32 v195, 0x190, v198
	v_lshl_add_u32 v230, v199, 4, v195
	v_cmp_gt_u32_e32 vcc, 16, v199
	v_mul_u32_u24_e32 v195, 0x500, v198
	v_lshlrev_b32_e32 v196, 7, v198
	v_add_u32_e32 v196, s76, v196
	s_nop 1
	v_cndmask_b32_e32 v195, v196, v195, vcc
	v_lshl_add_u32 v224, v199, 4, v195
	v_mov_b32_e32 v195, 0x2000
	v_mov_b32_e32 v196, 0x14000
	v_cndmask_b32_e32 v227, v195, v196, vcc
	v_add_u32_e32 v197, 0x200, v202
	v_mul_hi_u32 v198, v197, s62
	v_mul_u32_u24_e32 v195, 24, v198
	v_sub_u32_e32 v199, v197, v195
	v_mul_u32_u24_e32 v195, 0x190, v198
	v_lshl_add_u32 v231, v199, 4, v195
	v_cmp_gt_u32_e32 vcc, 16, v199
	v_mul_u32_u24_e32 v195, 0x500, v198
	v_lshlrev_b32_e32 v196, 7, v198
	v_add_u32_e32 v196, s76, v196
	s_nop 1
	v_cndmask_b32_e32 v195, v196, v195, vcc
	v_lshl_add_u32 v225, v199, 4, v195
	v_mov_b32_e32 v195, 0x2000
	v_mov_b32_e32 v196, 0x14000
	v_cndmask_b32_e32 v228, v195, v196, vcc
	v_add_u32_e32 v197, 0x400, v202
	v_mul_hi_u32 v198, v197, s62
	v_mul_u32_u24_e32 v195, 24, v198
	v_sub_u32_e32 v199, v197, v195
	v_mul_u32_u24_e32 v195, 0x190, v198
	v_lshl_add_u32 v232, v199, 4, v195
	v_cmp_gt_u32_e32 vcc, 16, v199
	v_mul_u32_u24_e32 v195, 0x500, v198
	v_lshlrev_b32_e32 v196, 7, v198
	v_add_u32_e32 v196, s76, v196
	s_nop 1
	v_cndmask_b32_e32 v195, v196, v195, vcc
	v_lshl_add_u32 v226, v199, 4, v195
	v_mov_b32_e32 v195, 0x2000
	v_mov_b32_e32 v196, 0x14000
	v_cndmask_b32_e32 v229, v195, v196, vcc
	v_mov_b32_e32 v197, v202
	v_lshrrev_b32_e32 v198, 3, v197
	v_and_b32_e32 v199, 7, v197
	v_mul_u32_u24_e32 v195, 0x1200, v198
	v_lshl_add_u32 v233, v199, 4, v195
	v_mul_u32_u24_e32 v195, 0x90, v198
	v_lshl_add_u32 v195, v199, 4, v195
	v_add_u32_e32 v235, 0x12c00, v195
	v_add_u32_e32 v197, 0x200, v202
	v_lshrrev_b32_e32 v198, 3, v197
	v_and_b32_e32 v199, 7, v197
	v_mul_u32_u24_e32 v195, 0x1200, v198
	v_lshl_add_u32 v234, v199, 4, v195
	v_mul_u32_u24_e32 v195, 0x90, v198
	v_lshl_add_u32 v195, v199, 4, v195
	v_add_u32_e32 v236, 0x12c00, v195
	v_mul_u32_u24_e32 v195, 0x190, v192
	v_lshl_add_u32 v237, v193, 4, v195
	v_mul_u32_u24_e32 v195, 0x90, v192
	v_lshl_add_u32 v195, v193, 3, v195
	v_add_u32_e32 v238, 0x12c00, v195
	global_load_dwordx4 v[204:207], v224, s[4:5]
	global_load_dwordx4 v[208:211], v225, s[4:5]
	global_load_dwordx4 v[212:215], v226, s[4:5]
	global_load_dwordx4 v[216:219], v233, s[8:9]
	global_load_dwordx4 v[220:223], v234, s[8:9]
	v_add_u32_e32 v224, v224, v227
	v_add_u32_e32 v225, v225, v228
	v_add_u32_e32 v226, v226, v229
	s_add_u32 s8, s8, 0x80
	s_addc_u32 s9, s9, 0
	v_mov_b32_e32 v48, 0
	v_mov_b32_e32 v49, 0
	v_mov_b32_e32 v50, 0
	v_mov_b32_e32 v51, 0
	v_mov_b32_e32 v52, 0
	v_mov_b32_e32 v53, 0
	v_mov_b32_e32 v54, 0
	v_mov_b32_e32 v55, 0
	v_mov_b32_e32 v56, 0
	v_mov_b32_e32 v57, 0
	v_mov_b32_e32 v58, 0
	v_mov_b32_e32 v59, 0
	v_mov_b32_e32 v60, 0
	v_mov_b32_e32 v61, 0
	v_mov_b32_e32 v62, 0
	v_mov_b32_e32 v63, 0
	v_mov_b32_e32 v64, 0
	v_mov_b32_e32 v65, 0
	v_mov_b32_e32 v66, 0
	v_mov_b32_e32 v67, 0
	v_mov_b32_e32 v68, 0
	v_mov_b32_e32 v69, 0
	v_mov_b32_e32 v70, 0
	v_mov_b32_e32 v71, 0
	v_mov_b32_e32 v72, 0
	v_mov_b32_e32 v73, 0
	v_mov_b32_e32 v74, 0
	v_mov_b32_e32 v75, 0
	v_mov_b32_e32 v76, 0
	v_mov_b32_e32 v77, 0
	v_mov_b32_e32 v78, 0
	v_mov_b32_e32 v79, 0
	v_mov_b32_e32 v80, 0
	v_mov_b32_e32 v81, 0
	v_mov_b32_e32 v82, 0
	v_mov_b32_e32 v83, 0
	v_mov_b32_e32 v84, 0
	v_mov_b32_e32 v85, 0
	v_mov_b32_e32 v86, 0
	v_mov_b32_e32 v87, 0
	v_mov_b32_e32 v88, 0
	v_mov_b32_e32 v89, 0
	v_mov_b32_e32 v90, 0
	v_mov_b32_e32 v91, 0
	v_mov_b32_e32 v92, 0
	v_mov_b32_e32 v93, 0
	v_mov_b32_e32 v94, 0
	v_mov_b32_e32 v95, 0
	v_mov_b32_e32 v96, 0
	v_mov_b32_e32 v97, 0
	v_mov_b32_e32 v98, 0
	v_mov_b32_e32 v99, 0
	v_mov_b32_e32 v100, 0
	v_mov_b32_e32 v101, 0
	v_mov_b32_e32 v102, 0
	v_mov_b32_e32 v103, 0
	v_mov_b32_e32 v104, 0
	v_mov_b32_e32 v105, 0
	v_mov_b32_e32 v106, 0
	v_mov_b32_e32 v107, 0
	v_mov_b32_e32 v108, 0
	v_mov_b32_e32 v109, 0
	v_mov_b32_e32 v110, 0
	v_mov_b32_e32 v111, 0
	v_mov_b32_e32 v242, 0xf149f2ca
	v_mov_b32_e32 v244, 0
	v_mov_b32_e32 v243, 0xf149f2ca
	v_mov_b32_e32 v245, 0
	s_waitcnt vmcnt(0)
	v_lshl_add_u32 v195, v194, 5, v192
	v_lshlrev_b32_e32 v195, 12, v195
	v_lshl_add_u32 v250, v193, 3, v195
	v_add_u32_e32 v251, 0x10000, v250
	ds_write_b128 v230, v[204:207]
	ds_write_b128 v231, v[208:211]
	ds_write_b128 v232, v[212:215]
	ds_write_b128 v235, v[216:219]
	ds_write_b128 v236, v[220:223]
	s_waitcnt lgkmcnt(0)
	global_load_dwordx4 v[204:207], v224, s[4:5]
	global_load_dwordx4 v[208:211], v225, s[4:5]
	global_load_dwordx4 v[212:215], v226, s[4:5]
	global_load_dwordx4 v[216:219], v233, s[8:9]
	global_load_dwordx4 v[220:223], v234, s[8:9]
	s_barrier
; template <int DK>
; DI void dense_attn_item(LAS unsigned char* lds, const bf16_t* Qb, int ldq, const bf16_t* Kb, int ldk, const bf16_t* Kpe, const bf16_t* Vt, int nkeys, float sl2, bf16_t* Ob) {
;     ...
;     for (int kt = 0; kt < ntiles; ++kt) {
;         const int cur = kt & 1;
;         if (kt + 1 < ntiles) DA_LOAD((kt + 1) * 64);
;         const LAS unsigned char* kb_ = lds + cur * KTILE; const LAS unsigned char* vb_ = lds + 2 * KTILE + cur * VTILE;
; #pragma unroll
;         for (int kc = 0; kc < 2; ++kc) {
;             f32x4 sacc[2][2];
; #pragma unroll
;             for (int kb = 0; kb < 2; ++kb) {
;                 sacc[0][kb] = (f32x4){0.f, 0.f, 0.f, 0.f}; sacc[1][kb] = (f32x4){0.f, 0.f, 0.f, 0.f};
; #pragma unroll
;                 for (int kh = 0; kh < KS / 2; ++kh) {
;                     const bf16x8 k0 = *(const LAS bf16x8*)(kb_ + ((2 * kc + kb) * 16 + r16) * KROW + (2 * kh) * 64 + q4 * 16);
;                     const bf16x8 k1 = *(const LAS bf16x8*)(kb_ + ((2 * kc + kb) * 16 + r16) * KROW + (2 * kh + 1) * 64 + q4 * 16);
;                     __builtin_amdgcn_s_setprio(1);
;                     sacc[0][kb] = MFMA16(k0, qf[0][2 * kh], sacc[0][kb]); sacc[1][kb] = MFMA16(k0, qf[1][2 * kh], sacc[1][kb]);
;                     sacc[0][kb] = MFMA16(k1, qf[0][2 * kh + 1], sacc[0][kb]); sacc[1][kb] = MFMA16(k1, qf[1][2 * kh + 1], sacc[1][kb]);
;                     __builtin_amdgcn_s_setprio(0);
;                 }
;             }
;             bf16x8 pb[2];
; #pragma unroll
;             for (int qg = 0; qg < 2; ++qg) {
;                 float mx = fmaxf(fmaxf(fmaxf(sacc[qg][0][0], sacc[qg][0][1]), fmaxf(sacc[qg][0][2], sacc[qg][0][3])), fmaxf(fmaxf(sacc[qg][1][0], sacc[qg][1][1]), fmaxf(sacc[qg][1][2], sacc[qg][1][3])));
;                 mx = fmaxf(mx, __shfl_xor(mx, 16)); mx = fmaxf(mx, __shfl_xor(mx, 32));
;                 const float mnew = fmaxf(mrun[qg], mx * sl2), alpha = fast_exp2(mrun[qg] - mnew);
;                 mrun[qg] = mnew;
;                 float ps = 0.f;
; #pragma unroll
;                 for (int kb = 0; kb < 2; ++kb)
; #pragma unroll
;                     for (int j = 0; j < 4; ++j) { const float pv = fast_exp2(sacc[qg][kb][j] * sl2 - mnew); sacc[qg][kb][j] = pv; ps += pv; }
;                 lsum[qg] = lsum[qg] * alpha + ps;
; #pragma unroll
;                 for (int d = 0; d < 8; ++d) oacc[qg][d] *= alpha;
	v_mov_b32_e32 v239, v237
	ds_read_b128 v[144:147], v239 offset:0
	ds_read_b128 v[148:151], v239 offset:64
	ds_read_b128 v[152:155], v239 offset:128
	ds_read_b128 v[156:159], v239 offset:192
	ds_read_b128 v[160:163], v239 offset:256
	ds_read_b128 v[164:167], v239 offset:320
	s_waitcnt lgkmcnt(5)
	v_mfma_f32_16x16x32_bf16 v[112:115], v[144:147], v[0:3], 0
	v_mfma_f32_16x16x32_bf16 v[120:123], v[144:147], v[24:27], 0
	s_waitcnt lgkmcnt(4)
	v_mfma_f32_16x16x32_bf16 v[112:115], v[148:151], v[4:7], v[112:115]
	v_mfma_f32_16x16x32_bf16 v[120:123], v[148:151], v[28:31], v[120:123]
	s_waitcnt lgkmcnt(3)
	v_mfma_f32_16x16x32_bf16 v[112:115], v[152:155], v[8:11], v[112:115]
	v_mfma_f32_16x16x32_bf16 v[120:123], v[152:155], v[32:35], v[120:123]
	s_waitcnt lgkmcnt(2)
	v_mfma_f32_16x16x32_bf16 v[112:115], v[156:159], v[12:15], v[112:115]
	v_mfma_f32_16x16x32_bf16 v[120:123], v[156:159], v[36:39], v[120:123]
	s_waitcnt lgkmcnt(1)
	v_mfma_f32_16x16x32_bf16 v[112:115], v[160:163], v[16:19], v[112:115]
	v_mfma_f32_16x16x32_bf16 v[120:123], v[160:163], v[40:43], v[120:123]
	s_waitcnt lgkmcnt(0)
	v_mfma_f32_16x16x32_bf16 v[112:115], v[164:167], v[20:23], v[112:115]
	v_mfma_f32_16x16x32_bf16 v[120:123], v[164:167], v[44:47], v[120:123]
	ds_read_b128 v[144:147], v239 offset:6400
	ds_read_b128 v[148:151], v239 offset:6464
	ds_read_b128 v[152:155], v239 offset:6528
	ds_read_b128 v[156:159], v239 offset:6592
	ds_read_b128 v[160:163], v239 offset:6656
	ds_read_b128 v[164:167], v239 offset:6720
	s_waitcnt lgkmcnt(5)
	v_mfma_f32_16x16x32_bf16 v[116:119], v[144:147], v[0:3], 0
	v_mfma_f32_16x16x32_bf16 v[124:127], v[144:147], v[24:27], 0
	s_waitcnt lgkmcnt(4)
	v_mfma_f32_16x16x32_bf16 v[116:119], v[148:151], v[4:7], v[116:119]
	v_mfma_f32_16x16x32_bf16 v[124:127], v[148:151], v[28:31], v[124:127]
	s_waitcnt lgkmcnt(3)
	v_mfma_f32_16x16x32_bf16 v[116:119], v[152:155], v[8:11], v[116:119]
	v_mfma_f32_16x16x32_bf16 v[124:127], v[152:155], v[32:35], v[124:127]
	s_waitcnt lgkmcnt(2)
	v_mfma_f32_16x16x32_bf16 v[116:119], v[156:159], v[12:15], v[116:119]
	v_mfma_f32_16x16x32_bf16 v[124:127], v[156:159], v[36:39], v[124:127]
	s_waitcnt lgkmcnt(1)
	v_mfma_f32_16x16x32_bf16 v[116:119], v[160:163], v[16:19], v[116:119]
	v_mfma_f32_16x16x32_bf16 v[124:127], v[160:163], v[40:43], v[124:127]
	s_waitcnt lgkmcnt(0)
	v_mfma_f32_16x16x32_bf16 v[116:119], v[164:167], v[20:23], v[116:119]
	v_mfma_f32_16x16x32_bf16 v[124:127], v[164:167], v[44:47], v[124:127]
	s_mov_b32 s23, 0
	s_mov_b32 s27, 0
dn0_top:
	s_add_u32 s57, s27, 1
	s_cmp_eq_u32 s57, 3
	s_cselect_b32 s57, 0, s57
	s_mul_i32 s36, s27, 0x6400
	s_mul_i32 s54, s27, 0x4800
	s_mul_i32 s37, s57, 0x6400
	s_mul_i32 s56, s57, 0x4800
	v_add_u32_e32 v239, s36, v237
	v_add_u32_e32 v240, s37, v237
	v_add_u32_e32 v241, s54, v238
	v_add_u32_e32 v196, s37, v230
	v_add_u32_e32 v197, s37, v231
	v_add_u32_e32 v198, s37, v232
	v_add_u32_e32 v199, s56, v235
	v_add_u32_e32 v200, s56, v236
	v_add_u32_e32 v224, v224, v227
	v_add_u32_e32 v225, v225, v228
	v_add_u32_e32 v226, v226, v229
	s_add_u32 s8, s8, 0x80
	s_addc_u32 s9, s9, 0
	s_waitcnt vmcnt(0)
	ds_write_b128 v196, v[204:207]
	ds_write_b128 v197, v[208:211]
	ds_write_b128 v198, v[212:215]
	ds_write_b128 v199, v[216:219]
	ds_write_b128 v200, v[220:223]
	ds_read_b128 v[144:147], v239 offset:12800
	ds_read_b128 v[148:151], v239 offset:12864
	ds_read_b128 v[152:155], v239 offset:12928
	ds_read_b128 v[156:159], v239 offset:12992
	ds_read_b128 v[160:163], v239 offset:13056
	ds_read_b128 v[164:167], v239 offset:13120
	v_max3_f32 v193, v112, v113, v114
	v_max3_f32 v195, v120, v121, v122
	v_max3_f32 v192, v115, v116, v117
	v_max3_f32 v194, v123, v124, v125
	v_max3_f32 v193, v193, v118, v119
	v_max3_f32 v195, v195, v126, v127
	v_max_f32_e32 v193, v193, v192
	v_max_f32_e32 v195, v195, v194
	v_mov_b32_e32 v192, v193
	v_mov_b32_e32 v194, v195
	s_nop 1
	v_permlane16_swap_b32_e32 v193, v192
	s_waitcnt lgkmcnt(5)
	global_load_dwordx4 v[204:207], v224, s[4:5]
	global_load_dwordx4 v[208:211], v225, s[4:5]
	global_load_dwordx4 v[212:215], v226, s[4:5]
	global_load_dwordx4 v[216:219], v233, s[8:9]
	global_load_dwordx4 v[220:223], v234, s[8:9]
	v_mfma_f32_16x16x32_bf16 v[128:131], v[144:147], v[0:3], 0
	v_permlane16_swap_b32_e32 v195, v194
	v_max_f32_e32 v193, v193, v192
	v_max_f32_e32 v195, v195, v194
	v_mfma_f32_16x16x32_bf16 v[136:139], v[144:147], v[24:27], 0
	v_mov_b32_e32 v192, v193
	v_mov_b32_e32 v194, v195
	s_nop 1
	ds_read_b128 v[144:147], v239 offset:19200
	s_waitcnt lgkmcnt(5)
	v_mfma_f32_16x16x32_bf16 v[128:131], v[148:151], v[4:7], v[128:131]
	v_permlane32_swap_b32_e32 v193, v192
	v_permlane32_swap_b32_e32 v195, v194
	v_max_f32_e32 v193, v193, v192
	v_mfma_f32_16x16x32_bf16 v[136:139], v[148:151], v[28:31], v[136:139]
	v_max_f32_e32 v195, v195, v194
	v_mul_f32_e32 v193, s22, v193
	v_mul_f32_e32 v195, s22, v195
	ds_read_b128 v[148:151], v239 offset:19264
	s_waitcnt lgkmcnt(5)
	v_mfma_f32_16x16x32_bf16 v[128:131], v[152:155], v[8:11], v[128:131]
	v_max_f32_e32 v192, v242, v193
	v_max_f32_e32 v194, v243, v195
	v_sub_f32_e32 v193, v192, v242
	v_mfma_f32_16x16x32_bf16 v[136:139], v[152:155], v[32:35], v[136:139]
	v_sub_f32_e32 v195, v194, v243
	v_cmp_gt_f32_e64 s[68:69], v193, s29
	v_cmp_gt_f32_e64 s[0:1], v195, s29
	ds_read_b128 v[152:155], v239 offset:19328
	s_waitcnt lgkmcnt(5)
	v_mfma_f32_16x16x32_bf16 v[128:131], v[156:159], v[12:15], v[128:131]
	s_cmp_lg_u64 s[68:69], 0
	s_cselect_b64 s[68:69], -1, 0
	s_cmp_lg_u64 s[0:1], 0
	v_mfma_f32_16x16x32_bf16 v[136:139], v[156:159], v[36:39], v[136:139]
	s_cselect_b64 s[0:1], -1, 0
	v_cndmask_b32_e64 v192, v242, v192, s[68:69]
	v_cndmask_b32_e64 v194, v243, v194, s[0:1]
	ds_read_b128 v[156:159], v239 offset:19392
	s_waitcnt lgkmcnt(5)
; #define LAS __attribute__((address_space(3)))
; DI unsigned cvt_pk_bf16(float lo, float hi) { unsigned r; asm volatile("v_cvt_pk_bf16_f32 %0, %1, %2" : "=v"(r) : "v"(lo), "v"(hi)); return r; }
; template <int DK>
; DI void dense_attn_item(LAS unsigned char* lds, const bf16_t* Qb, int ldq, const bf16_t* Kb, int ldk, const bf16_t* Kpe, const bf16_t* Vt, int nkeys, float sl2, bf16_t* Ob) {
;     ...
;                 float mx = fmaxf(fmaxf(fmaxf(sacc[qg][0][0], sacc[qg][0][1]), fmaxf(sacc[qg][0][2], sacc[qg][0][3])), fmaxf(fmaxf(sacc[qg][1][0], sacc[qg][1][1]), fmaxf(sacc[qg][1][2], sacc[qg][1][3])));
;                 mx = fmaxf(mx, __shfl_xor(mx, 16)); mx = fmaxf(mx, __shfl_xor(mx, 32));
;                 const float mnew = fmaxf(mrun[qg], mx * sl2), alpha = fast_exp2(mrun[qg] - mnew);
;                 mrun[qg] = mnew;
;                 float ps = 0.f;
; #pragma unroll
;                 for (int kb = 0; kb < 2; ++kb)
; #pragma unroll
;                     for (int j = 0; j < 4; ++j) { const float pv = fast_exp2(sacc[qg][kb][j] * sl2 - mnew); sacc[qg][kb][j] = pv; ps += pv; }
;                 lsum[qg] = lsum[qg] * alpha + ps;
; #pragma unroll
;                 for (int d = 0; d < 8; ++d) oacc[qg][d] *= alpha;
;                 u32x4 w; w.x = cvt_pk_bf16(sacc[qg][0][0], sacc[qg][0][1]); w.y = cvt_pk_bf16(sacc[qg][0][2], sacc[qg][0][3]);
;                 w.z = cvt_pk_bf16(sacc[qg][1][0], sacc[qg][1][1]); w.w = cvt_pk_bf16(sacc[qg][1][2], sacc[qg][1][3]);
;                 pb[qg] = __builtin_bit_cast(bf16x8, w);
;             }
; #pragma unroll
;             for (int dh = 0; dh < 4; ++dh) {
;                 bf16x8 vfr[2];
; #pragma unroll
;                 for (int d4 = 0; d4 < 2; ++d4) {
;                     const int d = dh * 2 + d4;
;                     const u32x2 lo = *(const LAS u32x2*)(vb_ + (d * 16 + r16) * VROW + (kc * 32 + q4 * 4) * 2);
;                     const u32x2 hi = *(const LAS u32x2*)(vb_ + (d * 16 + r16) * VROW + (kc * 32 + 16 + q4 * 4) * 2);
;                     u32x4 w; w.x = lo.x; w.y = lo.y; w.z = hi.x; w.w = hi.y;
;                     vfr[d4] = __builtin_bit_cast(bf16x8, w);
;                 }
;                 __builtin_amdgcn_s_setprio(1);
; #pragma unroll
;                 for (int d4 = 0; d4 < 2; ++d4) { const int d = dh * 2 + d4; oacc[0][d] = MFMA16(vfr[d4], pb[0], oacc[0][d]); oacc[1][d] = MFMA16(vfr[d4], pb[1], oacc[1][d]); }
	v_mfma_f32_16x16x32_bf16 v[128:131], v[160:163], v[16:19], v[128:131]
	v_sub_f32_e32 v193, v242, v192
	v_sub_f32_e32 v195, v243, v194
	v_exp_f32_e32 v246, v193
	v_mfma_f32_16x16x32_bf16 v[136:139], v[160:163], v[40:43], v[136:139]
	v_exp_f32_e32 v248, v195
	v_mov_b32_e32 v242, v192
	v_mov_b32_e32 v243, v194
	ds_read_b128 v[160:163], v239 offset:19456
	s_waitcnt lgkmcnt(5)
	v_mfma_f32_16x16x32_bf16 v[128:131], v[164:167], v[20:23], v[128:131]
	v_pk_fma_f32 v[112:113], v[112:113], v[254:255], v[192:193] op_sel_hi:[1,0,0] neg_lo:[0,0,1] neg_hi:[0,0,1]
	v_pk_fma_f32 v[120:121], v[120:121], v[254:255], v[194:195] op_sel_hi:[1,0,0] neg_lo:[0,0,1] neg_hi:[0,0,1]
	v_pk_fma_f32 v[114:115], v[114:115], v[254:255], v[192:193] op_sel_hi:[1,0,0] neg_lo:[0,0,1] neg_hi:[0,0,1]
	v_mfma_f32_16x16x32_bf16 v[136:139], v[164:167], v[44:47], v[136:139]
	v_pk_fma_f32 v[122:123], v[122:123], v[254:255], v[194:195] op_sel_hi:[1,0,0] neg_lo:[0,0,1] neg_hi:[0,0,1]
	v_pk_fma_f32 v[116:117], v[116:117], v[254:255], v[192:193] op_sel_hi:[1,0,0] neg_lo:[0,0,1] neg_hi:[0,0,1]
	v_pk_fma_f32 v[124:125], v[124:125], v[254:255], v[194:195] op_sel_hi:[1,0,0] neg_lo:[0,0,1] neg_hi:[0,0,1]
	ds_read_b128 v[164:167], v239 offset:19520
	s_waitcnt lgkmcnt(5)
	v_mfma_f32_16x16x32_bf16 v[132:135], v[144:147], v[0:3], 0
	v_pk_fma_f32 v[118:119], v[118:119], v[254:255], v[192:193] op_sel_hi:[1,0,0] neg_lo:[0,0,1] neg_hi:[0,0,1]
	v_pk_fma_f32 v[126:127], v[126:127], v[254:255], v[194:195] op_sel_hi:[1,0,0] neg_lo:[0,0,1] neg_hi:[0,0,1]
	v_exp_f32_e32 v112, v112
	v_mfma_f32_16x16x32_bf16 v[140:143], v[144:147], v[24:27], 0
	v_exp_f32_e32 v120, v120
	v_exp_f32_e32 v113, v113
	v_exp_f32_e32 v121, v121
	ds_read_b64 v[168:169], v241 offset:0
	ds_read_b64 v[170:171], v241 offset:32
	s_waitcnt lgkmcnt(6)
	v_mfma_f32_16x16x32_bf16 v[132:135], v[148:151], v[4:7], v[132:135]
	v_exp_f32_e32 v114, v114
	v_exp_f32_e32 v122, v122
	v_exp_f32_e32 v115, v115
	v_mfma_f32_16x16x32_bf16 v[140:143], v[148:151], v[28:31], v[140:143]
	v_exp_f32_e32 v123, v123
	v_exp_f32_e32 v116, v116
	v_exp_f32_e32 v124, v124
	ds_read_b64 v[172:173], v241 offset:2304
	ds_read_b64 v[174:175], v241 offset:2336
	s_waitcnt lgkmcnt(7)
	v_mfma_f32_16x16x32_bf16 v[132:135], v[152:155], v[8:11], v[132:135]
	v_exp_f32_e32 v117, v117
	v_exp_f32_e32 v125, v125
	v_exp_f32_e32 v118, v118
	v_mfma_f32_16x16x32_bf16 v[140:143], v[152:155], v[32:35], v[140:143]
	v_exp_f32_e32 v126, v126
	v_exp_f32_e32 v119, v119
	v_exp_f32_e32 v127, v127
	ds_read_b64 v[176:177], v241 offset:4608
	ds_read_b64 v[178:179], v241 offset:4640
	s_waitcnt lgkmcnt(8)
	v_mfma_f32_16x16x32_bf16 v[132:135], v[156:159], v[12:15], v[132:135]
	v_pk_add_f32 v[196:197], v[112:113], v[114:115]
	v_pk_add_f32 v[198:199], v[120:121], v[122:123]
	v_pk_add_f32 v[196:197], v[196:197], v[116:117]
	v_mfma_f32_16x16x32_bf16 v[140:143], v[156:159], v[36:39], v[140:143]
	v_pk_add_f32 v[198:199], v[198:199], v[124:125]
	v_pk_add_f32 v[196:197], v[196:197], v[118:119]
	v_pk_add_f32 v[198:199], v[198:199], v[126:127]
	ds_read_b64 v[180:181], v241 offset:6912
	ds_read_b64 v[182:183], v241 offset:6944
	s_waitcnt lgkmcnt(9)
	v_mfma_f32_16x16x32_bf16 v[132:135], v[160:163], v[16:19], v[132:135]
	v_add_f32_e32 v193, v196, v197
	v_add_f32_e32 v195, v198, v199
	v_fma_f32 v244, v244, v246, v193
	v_mfma_f32_16x16x32_bf16 v[140:143], v[160:163], v[40:43], v[140:143]
	v_fma_f32 v245, v245, v248, v195
	v_cvt_pk_bf16_f32 v184, v112, v113
	v_cvt_pk_bf16_f32 v188, v120, v121
	s_waitcnt lgkmcnt(8)
	v_mfma_f32_16x16x32_bf16 v[132:135], v[164:167], v[20:23], v[132:135]
	v_cvt_pk_bf16_f32 v185, v114, v115
	v_cvt_pk_bf16_f32 v189, v122, v123
	v_cvt_pk_bf16_f32 v186, v116, v117
	v_mfma_f32_16x16x32_bf16 v[140:143], v[164:167], v[44:47], v[140:143]
	v_cvt_pk_bf16_f32 v190, v124, v125
	v_cvt_pk_bf16_f32 v187, v118, v119
	v_cvt_pk_bf16_f32 v191, v126, v127
	s_or_b64 vcc, s[68:69], s[0:1]
	s_cbranch_vccz dn0_nr1
	v_pk_mul_f32 v[48:49], v[48:49], v[246:247] op_sel_hi:[1,0]
	v_pk_mul_f32 v[50:51], v[50:51], v[246:247] op_sel_hi:[1,0]
	v_pk_mul_f32 v[80:81], v[80:81], v[248:249] op_sel_hi:[1,0]
	v_pk_mul_f32 v[82:83], v[82:83], v[248:249] op_sel_hi:[1,0]
	s_waitcnt lgkmcnt(6)
	v_mfma_f32_16x16x32_bf16 v[48:51], v[168:171], v[184:187], v[48:51]
	v_pk_mul_f32 v[52:53], v[52:53], v[246:247] op_sel_hi:[1,0]
	v_pk_mul_f32 v[54:55], v[54:55], v[246:247] op_sel_hi:[1,0]
	v_mfma_f32_16x16x32_bf16 v[80:83], v[168:171], v[188:191], v[80:83]
	v_pk_mul_f32 v[84:85], v[84:85], v[248:249] op_sel_hi:[1,0]
	v_pk_mul_f32 v[86:87], v[86:87], v[248:249] op_sel_hi:[1,0]
	ds_read_b64 v[168:169], v241 offset:9216
	ds_read_b64 v[170:171], v241 offset:9248
	s_waitcnt lgkmcnt(6)
	v_mfma_f32_16x16x32_bf16 v[52:55], v[172:175], v[184:187], v[52:55]
	v_pk_mul_f32 v[56:57], v[56:57], v[246:247] op_sel_hi:[1,0]
	v_pk_mul_f32 v[58:59], v[58:59], v[246:247] op_sel_hi:[1,0]
	v_mfma_f32_16x16x32_bf16 v[84:87], v[172:175], v[188:191], v[84:87]
	v_pk_mul_f32 v[88:89], v[88:89], v[248:249] op_sel_hi:[1,0]
	v_pk_mul_f32 v[90:91], v[90:91], v[248:249] op_sel_hi:[1,0]
	ds_read_b64 v[172:173], v241 offset:11520
	ds_read_b64 v[174:175], v241 offset:11552
	s_waitcnt lgkmcnt(6)
	v_mfma_f32_16x16x32_bf16 v[56:59], v[176:179], v[184:187], v[56:59]
	v_pk_mul_f32 v[60:61], v[60:61], v[246:247] op_sel_hi:[1,0]
	v_pk_mul_f32 v[62:63], v[62:63], v[246:247] op_sel_hi:[1,0]
	v_mfma_f32_16x16x32_bf16 v[88:91], v[176:179], v[188:191], v[88:91]
	v_pk_mul_f32 v[92:93], v[92:93], v[248:249] op_sel_hi:[1,0]
	v_pk_mul_f32 v[94:95], v[94:95], v[248:249] op_sel_hi:[1,0]
	ds_read_b64 v[176:177], v241 offset:13824
	ds_read_b64 v[178:179], v241 offset:13856
	s_waitcnt lgkmcnt(6)
; #define LAS __attribute__((address_space(3)))
; DI unsigned cvt_pk_bf16(float lo, float hi) { unsigned r; asm volatile("v_cvt_pk_bf16_f32 %0, %1, %2" : "=v"(r) : "v"(lo), "v"(hi)); return r; }
; #define MFMA16(a, b, c) __builtin_amdgcn_mfma_f32_16x16x32_bf16((a), (b), (c), 0, 0, 0)
; template <int DK>
; DI void dense_attn_item(LAS unsigned char* lds, const bf16_t* Qb, int ldq, const bf16_t* Kb, int ldk, const bf16_t* Kpe, const bf16_t* Vt, int nkeys, float sl2, bf16_t* Ob) {
;     ...
;                 float mx = fmaxf(fmaxf(fmaxf(sacc[qg][0][0], sacc[qg][0][1]), fmaxf(sacc[qg][0][2], sacc[qg][0][3])), fmaxf(fmaxf(sacc[qg][1][0], sacc[qg][1][1]), fmaxf(sacc[qg][1][2], sacc[qg][1][3])));
;                 mx = fmaxf(mx, __shfl_xor(mx, 16)); mx = fmaxf(mx, __shfl_xor(mx, 32));
;                 const float mnew = fmaxf(mrun[qg], mx * sl2), alpha = fast_exp2(mrun[qg] - mnew);
;     ...
;                     for (int j = 0; j < 4; ++j) { const float pv = fast_exp2(sacc[qg][kb][j] * sl2 - mnew); sacc[qg][kb][j] = pv; ps += pv; }
;                 lsum[qg] = lsum[qg] * alpha + ps;
; #pragma unroll
;                 for (int d = 0; d < 8; ++d) oacc[qg][d] *= alpha;
;                 u32x4 w; w.x = cvt_pk_bf16(sacc[qg][0][0], sacc[qg][0][1]); w.y = cvt_pk_bf16(sacc[qg][0][2], sacc[qg][0][3]);
;                 w.z = cvt_pk_bf16(sacc[qg][1][0], sacc[qg][1][1]); w.w = cvt_pk_bf16(sacc[qg][1][2], sacc[qg][1][3]);
;                 pb[qg] = __builtin_bit_cast(bf16x8, w);
;             }
; #pragma unroll
;             for (int dh = 0; dh < 4; ++dh) {
;                 bf16x8 vfr[2];
; #pragma unroll
;                 for (int d4 = 0; d4 < 2; ++d4) {
;                     const int d = dh * 2 + d4;
;                     const u32x2 lo = *(const LAS u32x2*)(vb_ + (d * 16 + r16) * VROW + (kc * 32 + q4 * 4) * 2);
;                     const u32x2 hi = *(const LAS u32x2*)(vb_ + (d * 16 + r16) * VROW + (kc * 32 + 16 + q4 * 4) * 2);
;                     u32x4 w; w.x = lo.x; w.y = lo.y; w.z = hi.x; w.w = hi.y;
;                     vfr[d4] = __builtin_bit_cast(bf16x8, w);
;                 }
;                 __builtin_amdgcn_s_setprio(1);
; #pragma unroll
;                 for (int d4 = 0; d4 < 2; ++d4) { const int d = dh * 2 + d4; oacc[0][d] = MFMA16(vfr[d4], pb[0], oacc[0][d]); oacc[1][d] = MFMA16(vfr[d4], pb[1], oacc[1][d]); }
	v_mfma_f32_16x16x32_bf16 v[60:63], v[180:183], v[184:187], v[60:63]
	v_pk_mul_f32 v[64:65], v[64:65], v[246:247] op_sel_hi:[1,0]
	v_pk_mul_f32 v[66:67], v[66:67], v[246:247] op_sel_hi:[1,0]
	v_mfma_f32_16x16x32_bf16 v[92:95], v[180:183], v[188:191], v[92:95]
	v_pk_mul_f32 v[96:97], v[96:97], v[248:249] op_sel_hi:[1,0]
	v_pk_mul_f32 v[98:99], v[98:99], v[248:249] op_sel_hi:[1,0]
	ds_read_b64 v[180:181], v241 offset:16128
	ds_read_b64 v[182:183], v241 offset:16160
	s_waitcnt lgkmcnt(6)
	v_mfma_f32_16x16x32_bf16 v[64:67], v[168:171], v[184:187], v[64:67]
	v_pk_mul_f32 v[68:69], v[68:69], v[246:247] op_sel_hi:[1,0]
	v_pk_mul_f32 v[70:71], v[70:71], v[246:247] op_sel_hi:[1,0]
	v_mfma_f32_16x16x32_bf16 v[96:99], v[168:171], v[188:191], v[96:99]
	v_pk_mul_f32 v[100:101], v[100:101], v[248:249] op_sel_hi:[1,0]
	v_pk_mul_f32 v[102:103], v[102:103], v[248:249] op_sel_hi:[1,0]
	s_waitcnt lgkmcnt(4)
	v_mfma_f32_16x16x32_bf16 v[68:71], v[172:175], v[184:187], v[68:71]
	v_pk_mul_f32 v[72:73], v[72:73], v[246:247] op_sel_hi:[1,0]
	v_pk_mul_f32 v[74:75], v[74:75], v[246:247] op_sel_hi:[1,0]
	v_mfma_f32_16x16x32_bf16 v[100:103], v[172:175], v[188:191], v[100:103]
	v_pk_mul_f32 v[104:105], v[104:105], v[248:249] op_sel_hi:[1,0]
	v_pk_mul_f32 v[106:107], v[106:107], v[248:249] op_sel_hi:[1,0]
	s_waitcnt lgkmcnt(2)
	v_mfma_f32_16x16x32_bf16 v[72:75], v[176:179], v[184:187], v[72:75]
	v_pk_mul_f32 v[76:77], v[76:77], v[246:247] op_sel_hi:[1,0]
	v_pk_mul_f32 v[78:79], v[78:79], v[246:247] op_sel_hi:[1,0]
	v_mfma_f32_16x16x32_bf16 v[104:107], v[176:179], v[188:191], v[104:107]
	v_pk_mul_f32 v[108:109], v[108:109], v[248:249] op_sel_hi:[1,0]
	v_pk_mul_f32 v[110:111], v[110:111], v[248:249] op_sel_hi:[1,0]
	s_waitcnt lgkmcnt(0)
	v_mfma_f32_16x16x32_bf16 v[76:79], v[180:183], v[184:187], v[76:79]
	v_mfma_f32_16x16x32_bf16 v[108:111], v[180:183], v[188:191], v[108:111]
	s_branch dn0_jn1
dn0_nr1:
	s_nop 1
	s_waitcnt lgkmcnt(6)
	v_mfma_f32_16x16x32_bf16 v[48:51], v[168:171], v[184:187], v[48:51]
	v_mfma_f32_16x16x32_bf16 v[80:83], v[168:171], v[188:191], v[80:83]
	ds_read_b64 v[168:169], v241 offset:9216
	ds_read_b64 v[170:171], v241 offset:9248
	s_waitcnt lgkmcnt(6)
	v_mfma_f32_16x16x32_bf16 v[52:55], v[172:175], v[184:187], v[52:55]
	v_mfma_f32_16x16x32_bf16 v[84:87], v[172:175], v[188:191], v[84:87]
	ds_read_b64 v[172:173], v241 offset:11520
	ds_read_b64 v[174:175], v241 offset:11552
	s_waitcnt lgkmcnt(6)
	v_mfma_f32_16x16x32_bf16 v[56:59], v[176:179], v[184:187], v[56:59]
	v_mfma_f32_16x16x32_bf16 v[88:91], v[176:179], v[188:191], v[88:91]
	ds_read_b64 v[176:177], v241 offset:13824
	ds_read_b64 v[178:179], v241 offset:13856
	s_waitcnt lgkmcnt(6)
	v_mfma_f32_16x16x32_bf16 v[60:63], v[180:183], v[184:187], v[60:63]
	v_mfma_f32_16x16x32_bf16 v[92:95], v[180:183], v[188:191], v[92:95]
	ds_read_b64 v[180:181], v241 offset:16128
	ds_read_b64 v[182:183], v241 offset:16160
	s_waitcnt lgkmcnt(6)
	v_mfma_f32_16x16x32_bf16 v[64:67], v[168:171], v[184:187], v[64:67]
	v_mfma_f32_16x16x32_bf16 v[96:99], v[168:171], v[188:191], v[96:99]
	s_waitcnt lgkmcnt(4)
	v_mfma_f32_16x16x32_bf16 v[68:71], v[172:175], v[184:187], v[68:71]
	v_mfma_f32_16x16x32_bf16 v[100:103], v[172:175], v[188:191], v[100:103]
	s_waitcnt lgkmcnt(2)
	v_mfma_f32_16x16x32_bf16 v[72:75], v[176:179], v[184:187], v[72:75]
	v_mfma_f32_16x16x32_bf16 v[104:107], v[176:179], v[188:191], v[104:107]
	s_waitcnt lgkmcnt(0)
	v_mfma_f32_16x16x32_bf16 v[76:79], v[180:183], v[184:187], v[76:79]
	v_mfma_f32_16x16x32_bf16 v[108:111], v[180:183], v[188:191], v[108:111]
dn0_jn1:
	s_waitcnt lgkmcnt(0)
	s_barrier
	ds_read_b128 v[144:147], v240 offset:0
	ds_read_b128 v[148:151], v240 offset:64
	ds_read_b128 v[152:155], v240 offset:128
	ds_read_b128 v[156:159], v240 offset:192
	ds_read_b128 v[160:163], v240 offset:256
	ds_read_b128 v[164:167], v240 offset:320
	v_max3_f32 v193, v128, v129, v130
	v_max3_f32 v195, v136, v137, v138
	v_max3_f32 v192, v131, v132, v133
	v_max3_f32 v194, v139, v140, v141
	v_max3_f32 v193, v193, v134, v135
	v_max3_f32 v195, v195, v142, v143
	v_max_f32_e32 v193, v193, v192
	v_max_f32_e32 v195, v195, v194
	v_mov_b32_e32 v192, v193
	v_mov_b32_e32 v194, v195
	s_nop 1
	v_permlane16_swap_b32_e32 v193, v192
	s_waitcnt lgkmcnt(5)
	v_mfma_f32_16x16x32_bf16 v[112:115], v[144:147], v[0:3], 0
	v_permlane16_swap_b32_e32 v195, v194
	v_max_f32_e32 v193, v193, v192
	v_max_f32_e32 v195, v195, v194
	v_mfma_f32_16x16x32_bf16 v[120:123], v[144:147], v[24:27], 0
	v_mov_b32_e32 v192, v193
	v_mov_b32_e32 v194, v195
	s_nop 1
	ds_read_b128 v[144:147], v240 offset:6400
	s_waitcnt lgkmcnt(5)
	v_mfma_f32_16x16x32_bf16 v[112:115], v[148:151], v[4:7], v[112:115]
	v_permlane32_swap_b32_e32 v193, v192
	v_permlane32_swap_b32_e32 v195, v194
	v_max_f32_e32 v193, v193, v192
	v_mfma_f32_16x16x32_bf16 v[120:123], v[148:151], v[28:31], v[120:123]
	v_max_f32_e32 v195, v195, v194
	v_mul_f32_e32 v193, s22, v193
	v_mul_f32_e32 v195, s22, v195
	ds_read_b128 v[148:151], v240 offset:6464
	s_waitcnt lgkmcnt(5)
	v_mfma_f32_16x16x32_bf16 v[112:115], v[152:155], v[8:11], v[112:115]
	v_max_f32_e32 v192, v242, v193
	v_max_f32_e32 v194, v243, v195
	v_sub_f32_e32 v193, v192, v242
	v_mfma_f32_16x16x32_bf16 v[120:123], v[152:155], v[32:35], v[120:123]
	v_sub_f32_e32 v195, v194, v243
	v_cmp_gt_f32_e64 s[68:69], v193, s29
	v_cmp_gt_f32_e64 s[0:1], v195, s29
	ds_read_b128 v[152:155], v240 offset:6528
	s_waitcnt lgkmcnt(5)
	v_mfma_f32_16x16x32_bf16 v[112:115], v[156:159], v[12:15], v[112:115]
	s_cmp_lg_u64 s[68:69], 0
	s_cselect_b64 s[68:69], -1, 0
	s_cmp_lg_u64 s[0:1], 0
	v_mfma_f32_16x16x32_bf16 v[120:123], v[156:159], v[36:39], v[120:123]
	s_cselect_b64 s[0:1], -1, 0
	v_cndmask_b32_e64 v192, v242, v192, s[68:69]
	v_cndmask_b32_e64 v194, v243, v194, s[0:1]
	ds_read_b128 v[156:159], v240 offset:6592
	s_waitcnt lgkmcnt(5)
; #define LAS __attribute__((address_space(3)))
; DI unsigned cvt_pk_bf16(float lo, float hi) { unsigned r; asm volatile("v_cvt_pk_bf16_f32 %0, %1, %2" : "=v"(r) : "v"(lo), "v"(hi)); return r; }
; template <int DK>
; DI void dense_attn_item(LAS unsigned char* lds, const bf16_t* Qb, int ldq, const bf16_t* Kb, int ldk, const bf16_t* Kpe, const bf16_t* Vt, int nkeys, float sl2, bf16_t* Ob) {
;     ...
;                 float mx = fmaxf(fmaxf(fmaxf(sacc[qg][0][0], sacc[qg][0][1]), fmaxf(sacc[qg][0][2], sacc[qg][0][3])), fmaxf(fmaxf(sacc[qg][1][0], sacc[qg][1][1]), fmaxf(sacc[qg][1][2], sacc[qg][1][3])));
;                 mx = fmaxf(mx, __shfl_xor(mx, 16)); mx = fmaxf(mx, __shfl_xor(mx, 32));
;                 const float mnew = fmaxf(mrun[qg], mx * sl2), alpha = fast_exp2(mrun[qg] - mnew);
;                 mrun[qg] = mnew;
;                 float ps = 0.f;
; #pragma unroll
;                 for (int kb = 0; kb < 2; ++kb)
; #pragma unroll
;                     for (int j = 0; j < 4; ++j) { const float pv = fast_exp2(sacc[qg][kb][j] * sl2 - mnew); sacc[qg][kb][j] = pv; ps += pv; }
;                 lsum[qg] = lsum[qg] * alpha + ps;
; #pragma unroll
;                 for (int d = 0; d < 8; ++d) oacc[qg][d] *= alpha;
;                 u32x4 w; w.x = cvt_pk_bf16(sacc[qg][0][0], sacc[qg][0][1]); w.y = cvt_pk_bf16(sacc[qg][0][2], sacc[qg][0][3]);
;                 w.z = cvt_pk_bf16(sacc[qg][1][0], sacc[qg][1][1]); w.w = cvt_pk_bf16(sacc[qg][1][2], sacc[qg][1][3]);
;                 pb[qg] = __builtin_bit_cast(bf16x8, w);
;             }
; #pragma unroll
;             for (int dh = 0; dh < 4; ++dh) {
;                 bf16x8 vfr[2];
; #pragma unroll
;                 for (int d4 = 0; d4 < 2; ++d4) {
;                     const int d = dh * 2 + d4;
;                     const u32x2 lo = *(const LAS u32x2*)(vb_ + (d * 16 + r16) * VROW + (kc * 32 + q4 * 4) * 2);
;                     const u32x2 hi = *(const LAS u32x2*)(vb_ + (d * 16 + r16) * VROW + (kc * 32 + 16 + q4 * 4) * 2);
;                     u32x4 w; w.x = lo.x; w.y = lo.y; w.z = hi.x; w.w = hi.y;
;                     vfr[d4] = __builtin_bit_cast(bf16x8, w);
;                 }
;                 __builtin_amdgcn_s_setprio(1);
; #pragma unroll
;                 for (int d4 = 0; d4 < 2; ++d4) { const int d = dh * 2 + d4; oacc[0][d] = MFMA16(vfr[d4], pb[0], oacc[0][d]); oacc[1][d] = MFMA16(vfr[d4], pb[1], oacc[1][d]); }
	v_mfma_f32_16x16x32_bf16 v[112:115], v[160:163], v[16:19], v[112:115]
	v_sub_f32_e32 v193, v242, v192
	v_sub_f32_e32 v195, v243, v194
	v_exp_f32_e32 v246, v193
	v_mfma_f32_16x16x32_bf16 v[120:123], v[160:163], v[40:43], v[120:123]
	v_exp_f32_e32 v248, v195
	v_mov_b32_e32 v242, v192
	v_mov_b32_e32 v243, v194
	ds_read_b128 v[160:163], v240 offset:6656
	s_waitcnt lgkmcnt(5)
	v_mfma_f32_16x16x32_bf16 v[112:115], v[164:167], v[20:23], v[112:115]
	v_pk_fma_f32 v[128:129], v[128:129], v[254:255], v[192:193] op_sel_hi:[1,0,0] neg_lo:[0,0,1] neg_hi:[0,0,1]
	v_pk_fma_f32 v[136:137], v[136:137], v[254:255], v[194:195] op_sel_hi:[1,0,0] neg_lo:[0,0,1] neg_hi:[0,0,1]
	v_pk_fma_f32 v[130:131], v[130:131], v[254:255], v[192:193] op_sel_hi:[1,0,0] neg_lo:[0,0,1] neg_hi:[0,0,1]
	v_mfma_f32_16x16x32_bf16 v[120:123], v[164:167], v[44:47], v[120:123]
	v_pk_fma_f32 v[138:139], v[138:139], v[254:255], v[194:195] op_sel_hi:[1,0,0] neg_lo:[0,0,1] neg_hi:[0,0,1]
	v_pk_fma_f32 v[132:133], v[132:133], v[254:255], v[192:193] op_sel_hi:[1,0,0] neg_lo:[0,0,1] neg_hi:[0,0,1]
	v_pk_fma_f32 v[140:141], v[140:141], v[254:255], v[194:195] op_sel_hi:[1,0,0] neg_lo:[0,0,1] neg_hi:[0,0,1]
	ds_read_b128 v[164:167], v240 offset:6720
	s_waitcnt lgkmcnt(5)
	v_mfma_f32_16x16x32_bf16 v[116:119], v[144:147], v[0:3], 0
	v_pk_fma_f32 v[134:135], v[134:135], v[254:255], v[192:193] op_sel_hi:[1,0,0] neg_lo:[0,0,1] neg_hi:[0,0,1]
	v_pk_fma_f32 v[142:143], v[142:143], v[254:255], v[194:195] op_sel_hi:[1,0,0] neg_lo:[0,0,1] neg_hi:[0,0,1]
	v_exp_f32_e32 v128, v128
	v_mfma_f32_16x16x32_bf16 v[124:127], v[144:147], v[24:27], 0
	v_exp_f32_e32 v136, v136
	v_exp_f32_e32 v129, v129
	v_exp_f32_e32 v137, v137
	ds_read_b64 v[168:169], v241 offset:64
	ds_read_b64 v[170:171], v241 offset:96
	s_waitcnt lgkmcnt(6)
	v_mfma_f32_16x16x32_bf16 v[116:119], v[148:151], v[4:7], v[116:119]
	v_exp_f32_e32 v130, v130
	v_exp_f32_e32 v138, v138
	v_exp_f32_e32 v131, v131
	v_mfma_f32_16x16x32_bf16 v[124:127], v[148:151], v[28:31], v[124:127]
	v_exp_f32_e32 v139, v139
	v_exp_f32_e32 v132, v132
	v_exp_f32_e32 v140, v140
	ds_read_b64 v[172:173], v241 offset:2368
	ds_read_b64 v[174:175], v241 offset:2400
	s_waitcnt lgkmcnt(7)
	v_mfma_f32_16x16x32_bf16 v[116:119], v[152:155], v[8:11], v[116:119]
	v_exp_f32_e32 v133, v133
	v_exp_f32_e32 v141, v141
	v_exp_f32_e32 v134, v134
	v_mfma_f32_16x16x32_bf16 v[124:127], v[152:155], v[32:35], v[124:127]
	v_exp_f32_e32 v142, v142
	v_exp_f32_e32 v135, v135
	v_exp_f32_e32 v143, v143
	ds_read_b64 v[176:177], v241 offset:4672
	ds_read_b64 v[178:179], v241 offset:4704
	s_waitcnt lgkmcnt(8)
	v_mfma_f32_16x16x32_bf16 v[116:119], v[156:159], v[12:15], v[116:119]
	v_pk_add_f32 v[196:197], v[128:129], v[130:131]
	v_pk_add_f32 v[198:199], v[136:137], v[138:139]
	v_pk_add_f32 v[196:197], v[196:197], v[132:133]
	v_mfma_f32_16x16x32_bf16 v[124:127], v[156:159], v[36:39], v[124:127]
	v_pk_add_f32 v[198:199], v[198:199], v[140:141]
	v_pk_add_f32 v[196:197], v[196:197], v[134:135]
	v_pk_add_f32 v[198:199], v[198:199], v[142:143]
	ds_read_b64 v[180:181], v241 offset:6976
	ds_read_b64 v[182:183], v241 offset:7008
	s_waitcnt lgkmcnt(9)
	v_mfma_f32_16x16x32_bf16 v[116:119], v[160:163], v[16:19], v[116:119]
	v_add_f32_e32 v193, v196, v197
	v_add_f32_e32 v195, v198, v199
	v_fma_f32 v244, v244, v246, v193
	v_mfma_f32_16x16x32_bf16 v[124:127], v[160:163], v[40:43], v[124:127]
	v_fma_f32 v245, v245, v248, v195
	v_cvt_pk_bf16_f32 v184, v128, v129
	v_cvt_pk_bf16_f32 v188, v136, v137
	s_waitcnt lgkmcnt(8)
	v_mfma_f32_16x16x32_bf16 v[116:119], v[164:167], v[20:23], v[116:119]
	v_cvt_pk_bf16_f32 v185, v130, v131
	v_cvt_pk_bf16_f32 v189, v138, v139
	v_cvt_pk_bf16_f32 v186, v132, v133
	v_mfma_f32_16x16x32_bf16 v[124:127], v[164:167], v[44:47], v[124:127]
	v_cvt_pk_bf16_f32 v190, v140, v141
	v_cvt_pk_bf16_f32 v187, v134, v135
	v_cvt_pk_bf16_f32 v191, v142, v143
	s_or_b64 vcc, s[68:69], s[0:1]
	s_cbranch_vccz dn0_nr2
	v_pk_mul_f32 v[48:49], v[48:49], v[246:247] op_sel_hi:[1,0]
	v_pk_mul_f32 v[50:51], v[50:51], v[246:247] op_sel_hi:[1,0]
	v_pk_mul_f32 v[80:81], v[80:81], v[248:249] op_sel_hi:[1,0]
	v_pk_mul_f32 v[82:83], v[82:83], v[248:249] op_sel_hi:[1,0]
	s_waitcnt lgkmcnt(6)
	v_mfma_f32_16x16x32_bf16 v[48:51], v[168:171], v[184:187], v[48:51]
	v_pk_mul_f32 v[52:53], v[52:53], v[246:247] op_sel_hi:[1,0]
	v_pk_mul_f32 v[54:55], v[54:55], v[246:247] op_sel_hi:[1,0]
	v_mfma_f32_16x16x32_bf16 v[80:83], v[168:171], v[188:191], v[80:83]
	v_pk_mul_f32 v[84:85], v[84:85], v[248:249] op_sel_hi:[1,0]
	v_pk_mul_f32 v[86:87], v[86:87], v[248:249] op_sel_hi:[1,0]
	ds_read_b64 v[168:169], v241 offset:9280
	ds_read_b64 v[170:171], v241 offset:9312
	s_waitcnt lgkmcnt(6)
	v_mfma_f32_16x16x32_bf16 v[52:55], v[172:175], v[184:187], v[52:55]
	v_pk_mul_f32 v[56:57], v[56:57], v[246:247] op_sel_hi:[1,0]
	v_pk_mul_f32 v[58:59], v[58:59], v[246:247] op_sel_hi:[1,0]
	v_mfma_f32_16x16x32_bf16 v[84:87], v[172:175], v[188:191], v[84:87]
	v_pk_mul_f32 v[88:89], v[88:89], v[248:249] op_sel_hi:[1,0]
	v_pk_mul_f32 v[90:91], v[90:91], v[248:249] op_sel_hi:[1,0]
	ds_read_b64 v[172:173], v241 offset:11584
	ds_read_b64 v[174:175], v241 offset:11616
	s_waitcnt lgkmcnt(6)
	v_mfma_f32_16x16x32_bf16 v[56:59], v[176:179], v[184:187], v[56:59]
	v_pk_mul_f32 v[60:61], v[60:61], v[246:247] op_sel_hi:[1,0]
	v_pk_mul_f32 v[62:63], v[62:63], v[246:247] op_sel_hi:[1,0]
	v_mfma_f32_16x16x32_bf16 v[88:91], v[176:179], v[188:191], v[88:91]
	v_pk_mul_f32 v[92:93], v[92:93], v[248:249] op_sel_hi:[1,0]
	v_pk_mul_f32 v[94:95], v[94:95], v[248:249] op_sel_hi:[1,0]
	ds_read_b64 v[176:177], v241 offset:13888
	ds_read_b64 v[178:179], v241 offset:13920
	s_waitcnt lgkmcnt(6)
; #define LAS __attribute__((address_space(3)))
; DI unsigned cvt_pk_bf16(float lo, float hi) { unsigned r; asm volatile("v_cvt_pk_bf16_f32 %0, %1, %2" : "=v"(r) : "v"(lo), "v"(hi)); return r; }
; #define MFMA16(a, b, c) __builtin_amdgcn_mfma_f32_16x16x32_bf16((a), (b), (c), 0, 0, 0)
; DI float fast_exp2(float x) { return __builtin_amdgcn_exp2f(x); }
; template <int DK>
; DI void dense_attn_item(LAS unsigned char* lds, const bf16_t* Qb, int ldq, const bf16_t* Kb, int ldk, const bf16_t* Kpe, const bf16_t* Vt, int nkeys, float sl2, bf16_t* Ob) {
;     ...
;                     for (int j = 0; j < 4; ++j) { const float pv = fast_exp2(sacc[qg][kb][j] * sl2 - mnew); sacc[qg][kb][j] = pv; ps += pv; }
;                 lsum[qg] = lsum[qg] * alpha + ps;
; #pragma unroll
;                 for (int d = 0; d < 8; ++d) oacc[qg][d] *= alpha;
;                 u32x4 w; w.x = cvt_pk_bf16(sacc[qg][0][0], sacc[qg][0][1]); w.y = cvt_pk_bf16(sacc[qg][0][2], sacc[qg][0][3]);
;                 w.z = cvt_pk_bf16(sacc[qg][1][0], sacc[qg][1][1]); w.w = cvt_pk_bf16(sacc[qg][1][2], sacc[qg][1][3]);
;                 pb[qg] = __builtin_bit_cast(bf16x8, w);
;             }
; #pragma unroll
;             for (int dh = 0; dh < 4; ++dh) {
;                 bf16x8 vfr[2];
; #pragma unroll
;                 for (int d4 = 0; d4 < 2; ++d4) {
;                     const int d = dh * 2 + d4;
;                     const u32x2 lo = *(const LAS u32x2*)(vb_ + (d * 16 + r16) * VROW + (kc * 32 + q4 * 4) * 2);
;                     const u32x2 hi = *(const LAS u32x2*)(vb_ + (d * 16 + r16) * VROW + (kc * 32 + 16 + q4 * 4) * 2);
;                     u32x4 w; w.x = lo.x; w.y = lo.y; w.z = hi.x; w.w = hi.y;
;                     vfr[d4] = __builtin_bit_cast(bf16x8, w);
;                 }
;                 __builtin_amdgcn_s_setprio(1);
; #pragma unroll
;                 for (int d4 = 0; d4 < 2; ++d4) { const int d = dh * 2 + d4; oacc[0][d] = MFMA16(vfr[d4], pb[0], oacc[0][d]); oacc[1][d] = MFMA16(vfr[d4], pb[1], oacc[1][d]); }
	v_mfma_f32_16x16x32_bf16 v[60:63], v[180:183], v[184:187], v[60:63]
	v_pk_mul_f32 v[64:65], v[64:65], v[246:247] op_sel_hi:[1,0]
	v_pk_mul_f32 v[66:67], v[66:67], v[246:247] op_sel_hi:[1,0]
	v_mfma_f32_16x16x32_bf16 v[92:95], v[180:183], v[188:191], v[92:95]
	v_pk_mul_f32 v[96:97], v[96:97], v[248:249] op_sel_hi:[1,0]
	v_pk_mul_f32 v[98:99], v[98:99], v[248:249] op_sel_hi:[1,0]
	ds_read_b64 v[180:181], v241 offset:16192
	ds_read_b64 v[182:183], v241 offset:16224
	s_waitcnt lgkmcnt(6)
	v_mfma_f32_16x16x32_bf16 v[64:67], v[168:171], v[184:187], v[64:67]
	v_pk_mul_f32 v[68:69], v[68:69], v[246:247] op_sel_hi:[1,0]
	v_pk_mul_f32 v[70:71], v[70:71], v[246:247] op_sel_hi:[1,0]
	v_mfma_f32_16x16x32_bf16 v[96:99], v[168:171], v[188:191], v[96:99]
	v_pk_mul_f32 v[100:101], v[100:101], v[248:249] op_sel_hi:[1,0]
	v_pk_mul_f32 v[102:103], v[102:103], v[248:249] op_sel_hi:[1,0]
	s_waitcnt lgkmcnt(4)
	v_mfma_f32_16x16x32_bf16 v[68:71], v[172:175], v[184:187], v[68:71]
	v_pk_mul_f32 v[72:73], v[72:73], v[246:247] op_sel_hi:[1,0]
	v_pk_mul_f32 v[74:75], v[74:75], v[246:247] op_sel_hi:[1,0]
	v_mfma_f32_16x16x32_bf16 v[100:103], v[172:175], v[188:191], v[100:103]
	v_pk_mul_f32 v[104:105], v[104:105], v[248:249] op_sel_hi:[1,0]
	v_pk_mul_f32 v[106:107], v[106:107], v[248:249] op_sel_hi:[1,0]
	s_waitcnt lgkmcnt(2)
	v_mfma_f32_16x16x32_bf16 v[72:75], v[176:179], v[184:187], v[72:75]
	v_pk_mul_f32 v[76:77], v[76:77], v[246:247] op_sel_hi:[1,0]
	v_pk_mul_f32 v[78:79], v[78:79], v[246:247] op_sel_hi:[1,0]
	v_mfma_f32_16x16x32_bf16 v[104:107], v[176:179], v[188:191], v[104:107]
	v_pk_mul_f32 v[108:109], v[108:109], v[248:249] op_sel_hi:[1,0]
	v_pk_mul_f32 v[110:111], v[110:111], v[248:249] op_sel_hi:[1,0]
	s_waitcnt lgkmcnt(0)
	v_mfma_f32_16x16x32_bf16 v[76:79], v[180:183], v[184:187], v[76:79]
	v_mfma_f32_16x16x32_bf16 v[108:111], v[180:183], v[188:191], v[108:111]
	s_branch dn0_jn2
dn0_nr2:
	s_nop 1
	s_waitcnt lgkmcnt(6)
	v_mfma_f32_16x16x32_bf16 v[48:51], v[168:171], v[184:187], v[48:51]
	v_mfma_f32_16x16x32_bf16 v[80:83], v[168:171], v[188:191], v[80:83]
	ds_read_b64 v[168:169], v241 offset:9280
	ds_read_b64 v[170:171], v241 offset:9312
	s_waitcnt lgkmcnt(6)
	v_mfma_f32_16x16x32_bf16 v[52:55], v[172:175], v[184:187], v[52:55]
	v_mfma_f32_16x16x32_bf16 v[84:87], v[172:175], v[188:191], v[84:87]
	ds_read_b64 v[172:173], v241 offset:11584
	ds_read_b64 v[174:175], v241 offset:11616
	s_waitcnt lgkmcnt(6)
	v_mfma_f32_16x16x32_bf16 v[56:59], v[176:179], v[184:187], v[56:59]
	v_mfma_f32_16x16x32_bf16 v[88:91], v[176:179], v[188:191], v[88:91]
	ds_read_b64 v[176:177], v241 offset:13888
	ds_read_b64 v[178:179], v241 offset:13920
	s_waitcnt lgkmcnt(6)
	v_mfma_f32_16x16x32_bf16 v[60:63], v[180:183], v[184:187], v[60:63]
	v_mfma_f32_16x16x32_bf16 v[92:95], v[180:183], v[188:191], v[92:95]
	ds_read_b64 v[180:181], v241 offset:16192
	ds_read_b64 v[182:183], v241 offset:16224
	s_waitcnt lgkmcnt(6)
	v_mfma_f32_16x16x32_bf16 v[64:67], v[168:171], v[184:187], v[64:67]
	v_mfma_f32_16x16x32_bf16 v[96:99], v[168:171], v[188:191], v[96:99]
	s_waitcnt lgkmcnt(4)
	v_mfma_f32_16x16x32_bf16 v[68:71], v[172:175], v[184:187], v[68:71]
	v_mfma_f32_16x16x32_bf16 v[100:103], v[172:175], v[188:191], v[100:103]
	s_waitcnt lgkmcnt(2)
	v_mfma_f32_16x16x32_bf16 v[72:75], v[176:179], v[184:187], v[72:75]
	v_mfma_f32_16x16x32_bf16 v[104:107], v[176:179], v[188:191], v[104:107]
	s_waitcnt lgkmcnt(0)
	v_mfma_f32_16x16x32_bf16 v[76:79], v[180:183], v[184:187], v[76:79]
	v_mfma_f32_16x16x32_bf16 v[108:111], v[180:183], v[188:191], v[108:111]
; DI void st_bf16x4(bf16_t* p, f32x4 v) { u32x2 w; w.x = cvt_pk_bf16(v[0], v[1]); w.y = cvt_pk_bf16(v[2], v[3]); *(u32x2*)p = w; }
; template <int DK>
; DI void dense_attn_item(LAS unsigned char* lds, const bf16_t* Qb, int ldq, const bf16_t* Kb, int ldk, const bf16_t* Kpe, const bf16_t* Vt, int nkeys, float sl2, bf16_t* Ob) {
;     ...
;         if (kt + 1 < ntiles) DA_STORE(cur ^ 1);
;         __syncthreads();
;     }
; #pragma unroll
;     for (int qg = 0; qg < 2; ++qg) {
;         float l = lsum[qg]; l += __shfl_xor(l, 16); l += __shfl_xor(l, 32);
;         const float inv = 1.f / l;
;         bf16_t* op = Ob + (size_t)(wid * 32 + qg * 16 + r16) * DM + q4 * 4;
; #pragma unroll
;         for (int d = 0; d < 8; ++d) st_bf16x4(op + d * 16, oacc[qg][d] * inv);
;     }
dn0_jn2:
	s_mov_b32 s27, s57
	s_add_u32 s23, s23, 1
	s_cmp_lt_u32 s23, 36
	s_cbranch_scc1 dn0_top
	s_waitcnt vmcnt(0) lgkmcnt(0)
	v_mov_b32_e32 v192, v244
	v_mov_b32_e32 v193, v244
	v_mov_b32_e32 v194, v245
	v_mov_b32_e32 v195, v245
	s_nop 1
	v_permlane16_swap_b32_e32 v192, v193
	v_permlane16_swap_b32_e32 v194, v195
	v_add_f32_e32 v192, v192, v193
	v_add_f32_e32 v194, v194, v195
	v_mov_b32_e32 v193, v192
	v_mov_b32_e32 v195, v194
	s_nop 1
	v_permlane32_swap_b32_e32 v192, v193
	v_permlane32_swap_b32_e32 v194, v195
	v_add_f32_e32 v192, v192, v193
	v_add_f32_e32 v194, v194, v195
	v_rcp_f32_e32 v193, v192
	v_rcp_f32_e32 v195, v194
	s_nop 0
	v_fma_f32 v192, -v192, v193, 1.0
	v_fma_f32 v194, -v194, v195, 1.0
	v_fma_f32 v246, v192, v193, v193
	v_fma_f32 v248, v194, v195, v195
	v_pk_mul_f32 v[48:49], v[48:49], v[246:247] op_sel_hi:[1,0]
	v_pk_mul_f32 v[50:51], v[50:51], v[246:247] op_sel_hi:[1,0]
	v_cvt_pk_bf16_f32 v48, v48, v49
	v_cvt_pk_bf16_f32 v49, v50, v51
	global_store_dwordx2 v250, v[48:49], s[20:21] offset:0
	v_pk_mul_f32 v[52:53], v[52:53], v[246:247] op_sel_hi:[1,0]
	v_pk_mul_f32 v[54:55], v[54:55], v[246:247] op_sel_hi:[1,0]
	v_cvt_pk_bf16_f32 v52, v52, v53
	v_cvt_pk_bf16_f32 v53, v54, v55
	global_store_dwordx2 v250, v[52:53], s[20:21] offset:32
	v_pk_mul_f32 v[56:57], v[56:57], v[246:247] op_sel_hi:[1,0]
	v_pk_mul_f32 v[58:59], v[58:59], v[246:247] op_sel_hi:[1,0]
	v_cvt_pk_bf16_f32 v56, v56, v57
	v_cvt_pk_bf16_f32 v57, v58, v59
	global_store_dwordx2 v250, v[56:57], s[20:21] offset:64
	v_pk_mul_f32 v[60:61], v[60:61], v[246:247] op_sel_hi:[1,0]
	v_pk_mul_f32 v[62:63], v[62:63], v[246:247] op_sel_hi:[1,0]
	v_cvt_pk_bf16_f32 v60, v60, v61
	v_cvt_pk_bf16_f32 v61, v62, v63
	global_store_dwordx2 v250, v[60:61], s[20:21] offset:96
	v_pk_mul_f32 v[64:65], v[64:65], v[246:247] op_sel_hi:[1,0]
	v_pk_mul_f32 v[66:67], v[66:67], v[246:247] op_sel_hi:[1,0]
	v_cvt_pk_bf16_f32 v64, v64, v65
	v_cvt_pk_bf16_f32 v65, v66, v67
	global_store_dwordx2 v250, v[64:65], s[20:21] offset:128
	v_pk_mul_f32 v[68:69], v[68:69], v[246:247] op_sel_hi:[1,0]
	v_pk_mul_f32 v[70:71], v[70:71], v[246:247] op_sel_hi:[1,0]
	v_cvt_pk_bf16_f32 v68, v68, v69
	v_cvt_pk_bf16_f32 v69, v70, v71
	global_store_dwordx2 v250, v[68:69], s[20:21] offset:160
	v_pk_mul_f32 v[72:73], v[72:73], v[246:247] op_sel_hi:[1,0]
	v_pk_mul_f32 v[74:75], v[74:75], v[246:247] op_sel_hi:[1,0]
	v_cvt_pk_bf16_f32 v72, v72, v73
	v_cvt_pk_bf16_f32 v73, v74, v75
	global_store_dwordx2 v250, v[72:73], s[20:21] offset:192
	v_pk_mul_f32 v[76:77], v[76:77], v[246:247] op_sel_hi:[1,0]
	v_pk_mul_f32 v[78:79], v[78:79], v[246:247] op_sel_hi:[1,0]
	v_cvt_pk_bf16_f32 v76, v76, v77
	v_cvt_pk_bf16_f32 v77, v78, v79
	global_store_dwordx2 v250, v[76:77], s[20:21] offset:224
	v_pk_mul_f32 v[80:81], v[80:81], v[248:249] op_sel_hi:[1,0]
	v_pk_mul_f32 v[82:83], v[82:83], v[248:249] op_sel_hi:[1,0]
	v_cvt_pk_bf16_f32 v80, v80, v81
	v_cvt_pk_bf16_f32 v81, v82, v83
	global_store_dwordx2 v251, v[80:81], s[20:21] offset:0
	v_pk_mul_f32 v[84:85], v[84:85], v[248:249] op_sel_hi:[1,0]
	v_pk_mul_f32 v[86:87], v[86:87], v[248:249] op_sel_hi:[1,0]
	v_cvt_pk_bf16_f32 v84, v84, v85
	v_cvt_pk_bf16_f32 v85, v86, v87
	global_store_dwordx2 v251, v[84:85], s[20:21] offset:32
	v_pk_mul_f32 v[88:89], v[88:89], v[248:249] op_sel_hi:[1,0]
	v_pk_mul_f32 v[90:91], v[90:91], v[248:249] op_sel_hi:[1,0]
	v_cvt_pk_bf16_f32 v88, v88, v89
	v_cvt_pk_bf16_f32 v89, v90, v91
	global_store_dwordx2 v251, v[88:89], s[20:21] offset:64
	v_pk_mul_f32 v[92:93], v[92:93], v[248:249] op_sel_hi:[1,0]
	v_pk_mul_f32 v[94:95], v[94:95], v[248:249] op_sel_hi:[1,0]
	v_cvt_pk_bf16_f32 v92, v92, v93
	v_cvt_pk_bf16_f32 v93, v94, v95
	global_store_dwordx2 v251, v[92:93], s[20:21] offset:96
	v_pk_mul_f32 v[96:97], v[96:97], v[248:249] op_sel_hi:[1,0]
	v_pk_mul_f32 v[98:99], v[98:99], v[248:249] op_sel_hi:[1,0]
	v_cvt_pk_bf16_f32 v96, v96, v97
	v_cvt_pk_bf16_f32 v97, v98, v99
	global_store_dwordx2 v251, v[96:97], s[20:21] offset:128
	v_pk_mul_f32 v[100:101], v[100:101], v[248:249] op_sel_hi:[1,0]
	v_pk_mul_f32 v[102:103], v[102:103], v[248:249] op_sel_hi:[1,0]
	v_cvt_pk_bf16_f32 v100, v100, v101
	v_cvt_pk_bf16_f32 v101, v102, v103
	global_store_dwordx2 v251, v[100:101], s[20:21] offset:160
	v_pk_mul_f32 v[104:105], v[104:105], v[248:249] op_sel_hi:[1,0]
	v_pk_mul_f32 v[106:107], v[106:107], v[248:249] op_sel_hi:[1,0]
	v_cvt_pk_bf16_f32 v104, v104, v105
	v_cvt_pk_bf16_f32 v105, v106, v107
	global_store_dwordx2 v251, v[104:105], s[20:21] offset:192
	v_pk_mul_f32 v[108:109], v[108:109], v[248:249] op_sel_hi:[1,0]
	v_pk_mul_f32 v[110:111], v[110:111], v[248:249] op_sel_hi:[1,0]
	v_cvt_pk_bf16_f32 v108, v108, v109
	v_cvt_pk_bf16_f32 v109, v110, v111
	global_store_dwordx2 v251, v[108:109], s[20:21] offset:224
	v_mov_b32_e32 v133, 0
	s_waitcnt vmcnt(0)
	s_barrier
	s_and_saveexec_b64 s[0:1], s[24:25]
	s_cbranch_execz .LBB0_1145
	s_mov_b64 s[8:9], exec
	v_mbcnt_lo_u32_b32 v0, s8, 0
	v_mbcnt_hi_u32_b32 v0, s9, v0
	v_cmp_eq_u32_e32 vcc, 0, v0
	s_and_saveexec_b64 s[6:7], vcc
	s_cbranch_execz .LBB0_1144
	s_bcnt1_i32_b64 s8, s[8:9]
	v_mov_b32_e32 v1, s8
	global_atomic_add v1, v133, v1, s[42:43] sc0
	s_branch .LBB0_1144

; #define LAS __attribute__((address_space(3)))
; DI int otid() { int t = threadIdx.x; asm volatile("" : "+v"(t)); return t; }
; template <int DK>
; DI void dense_attn_item(LAS unsigned char* lds, const bf16_t* Qb, int ldq, const bf16_t* Kb, int ldk, const bf16_t* Kpe, const bf16_t* Vt, int nkeys, float sl2, bf16_t* Ob) {
;     const int tid = otid(), lane = tid & 63, wid = tid >> 6, r16 = lane & 15, q4 = lane >> 4;
;     constexpr int KS = DK / 32, KCH = DK / 8, KROW = DK * 2 + 16, KTILE = 64 * KROW, VROW = 144, VTILE = 128 * VROW, NKL = (64 * KCH) / 512;
;     bf16x8 qf[2][KS];
; #pragma unroll
;     for (int qg = 0; qg < 2; ++qg)
; #pragma unroll
;         for (int ks = 0; ks < KS; ++ks) qf[qg][ks] = *(const bf16x8*)(Qb + (size_t)(wid * 32 + qg * 16 + r16) * ldq + ks * 32 + q4 * 8);
;     f32x4 oacc[2][8];
; #pragma unroll
;     for (int qg = 0; qg < 2; ++qg)
; #pragma unroll
;         for (int d = 0; d < 8; ++d) oacc[qg][d] = (f32x4){0.f, 0.f, 0.f, 0.f};
;     float mrun[2] = {-1e30f, -1e30f}, lsum[2] = {0.f, 0.f};
;     u32x4 kst[NKL], vst[2];
;     const int ntiles = nkeys >> 6;
;     ...
;     DA_LOAD(0); DA_STORE(0);
;     __syncthreads();
; DI void phase_dense_attn(const Params& p, int l, LAS unsigned char* lds) {
;     ...
;     for (int it = blockIdx.x; it < n_lat + n_ctx; it += gridDim.x) {
;         if (it < n_lat) {
;             const int qb = it & 7, h = (it >> 3) % 5, b = it / 40; const size_t rowb = (size_t)b * RB, row0 = rowb + CL + qb * 256;
;             dense_attn_item<192>(lds, (const bf16_t*)(ws + WS_QM) + row0 * 960 + h * 192, 960, (const bf16_t*)(ws + WS_KM) + rowb * 640 + h * 128, 640, (const bf16_t*)(ws + WS_KPE) + rowb * 64,
;                                  (const bf16_t*)(ws + WS_VTM) + ((size_t)b * 640 + h * 128) * RB, RB, 0.07216878364870322f * 1.4426950408889634f, ymix + row0 * DM + 768 + h * 128);
.LBB0_2593:
	s_mul_hi_u32 s71, s0, 0x66666667
	s_lshr_b32 s71, s71, 4
	s_lshr_b32 s73, s0, 3
	s_mul_i32 s62, s71, 5
	s_sub_u32 s73, s73, s62
	s_and_b32 s62, s0, 7
	s_lshl_b32 s62, s62, 8
	s_mul_i32 s75, s71, 0x900
	s_add_u32 s74, s75, s62
	s_addk_i32 s74, 0x100
	s_mul_i32 s62, s74, 0x780
	s_mul_i32 s63, s73, 0x180
	s_add_u32 s62, s62, s63
	s_add_u32 s62, s62, 0x1a3a0000
	s_add_u32 s10, s50, s62
	s_addc_u32 s11, s51, 0
	s_mul_i32 s62, s75, 0x500
	s_lshl_b32 s63, s73, 8
	s_add_u32 s62, s62, s63
	s_add_u32 s62, s62, 0x1b480000
	s_add_u32 s4, s50, s62
	s_addc_u32 s5, s51, 0
	s_mul_i32 s62, s75, 0x480
	s_add_u32 s62, s62, s63
	s_sub_u32 s76, 0x167ff00, s62
	s_mul_i32 s62, s71, 0x280
	s_lshl_b32 s63, s73, 7
	s_add_u32 s62, s62, s63
	s_mul_i32 s62, s62, 0x1200
	s_add_u32 s62, s62, 0x1bfc0000
	s_add_u32 s8, s50, s62
	s_addc_u32 s9, s51, 0
	s_lshl_b32 s62, s74, 12
	s_lshl_b32 s63, s73, 8
	s_add_u32 s62, s62, s63
	s_add_u32 s62, s62, 0x1d9a0600
	s_add_u32 s20, s50, s62
	s_addc_u32 s21, s51, 0
	s_mov_b32 s22, 0x3dd53b94
	v_mov_b32_e32 v254, s22
	s_mov_b32 s29, 0x41000000
	v_and_b32_e32 v192, 15, v202
	v_bfe_u32 v193, v202, 4, 2
	v_lshrrev_b32_e32 v194, 6, v202
	v_lshl_add_u32 v195, v194, 5, v192
	v_mul_u32_u24_e32 v196, 0x780, v195
	v_lshl_add_u32 v250, v193, 4, v196
	v_add_u32_e32 v251, 0x7800, v250
	global_load_dwordx4 v[0:3], v250, s[10:11] offset:0
	global_load_dwordx4 v[4:7], v250, s[10:11] offset:64
	global_load_dwordx4 v[8:11], v250, s[10:11] offset:128
	global_load_dwordx4 v[12:15], v250, s[10:11] offset:192
	global_load_dwordx4 v[16:19], v250, s[10:11] offset:256
	global_load_dwordx4 v[20:23], v250, s[10:11] offset:320
	global_load_dwordx4 v[24:27], v251, s[10:11] offset:0
	global_load_dwordx4 v[28:31], v251, s[10:11] offset:64
	global_load_dwordx4 v[32:35], v251, s[10:11] offset:128
	global_load_dwordx4 v[36:39], v251, s[10:11] offset:192
	global_load_dwordx4 v[40:43], v251, s[10:11] offset:256
	global_load_dwordx4 v[44:47], v251, s[10:11] offset:320
	s_mov_b32 s62, 0xaaaaaab
	v_mov_b32_e32 v197, v202
	v_mul_hi_u32 v198, v197, s62
	v_mul_u32_u24_e32 v195, 24, v198
	v_sub_u32_e32 v199, v197, v195
	v_mul_u32_u24_e32 v195, 0x190, v198
	v_lshl_add_u32 v230, v199, 4, v195
	v_cmp_gt_u32_e32 vcc, 16, v199
	v_mul_u32_u24_e32 v195, 0x500, v198
	v_lshlrev_b32_e32 v196, 7, v198
	v_add_u32_e32 v196, s76, v196
	s_nop 1
	v_cndmask_b32_e32 v195, v196, v195, vcc
	v_lshl_add_u32 v224, v199, 4, v195
	v_mov_b32_e32 v195, 0x2000
	v_mov_b32_e32 v196, 0x14000
	v_cndmask_b32_e32 v227, v195, v196, vcc
	v_add_u32_e32 v197, 0x200, v202
	v_mul_hi_u32 v198, v197, s62
	v_mul_u32_u24_e32 v195, 24, v198
	v_sub_u32_e32 v199, v197, v195
	v_mul_u32_u24_e32 v195, 0x190, v198
	v_lshl_add_u32 v231, v199, 4, v195
	v_cmp_gt_u32_e32 vcc, 16, v199
	v_mul_u32_u24_e32 v195, 0x500, v198
	v_lshlrev_b32_e32 v196, 7, v198
	v_add_u32_e32 v196, s76, v196
	s_nop 1
	v_cndmask_b32_e32 v195, v196, v195, vcc
	v_lshl_add_u32 v225, v199, 4, v195
	v_mov_b32_e32 v195, 0x2000
	v_mov_b32_e32 v196, 0x14000
	v_cndmask_b32_e32 v228, v195, v196, vcc
	v_add_u32_e32 v197, 0x400, v202
	v_mul_hi_u32 v198, v197, s62
	v_mul_u32_u24_e32 v195, 24, v198
	v_sub_u32_e32 v199, v197, v195
	v_mul_u32_u24_e32 v195, 0x190, v198
	v_lshl_add_u32 v232, v199, 4, v195
	v_cmp_gt_u32_e32 vcc, 16, v199
	v_mul_u32_u24_e32 v195, 0x500, v198
	v_lshlrev_b32_e32 v196, 7, v198
	v_add_u32_e32 v196, s76, v196
	s_nop 1
	v_cndmask_b32_e32 v195, v196, v195, vcc
	v_lshl_add_u32 v226, v199, 4, v195
	v_mov_b32_e32 v195, 0x2000
	v_mov_b32_e32 v196, 0x14000
	v_cndmask_b32_e32 v229, v195, v196, vcc
	v_mov_b32_e32 v197, v202
	v_lshrrev_b32_e32 v198, 3, v197
	v_and_b32_e32 v199, 7, v197
	v_mul_u32_u24_e32 v195, 0x1200, v198
	v_lshl_add_u32 v233, v199, 4, v195
	v_mul_u32_u24_e32 v195, 0x90, v198
	v_lshl_add_u32 v195, v199, 4, v195
	v_add_u32_e32 v235, 0x12c00, v195
	v_add_u32_e32 v197, 0x200, v202
	v_lshrrev_b32_e32 v198, 3, v197
	v_and_b32_e32 v199, 7, v197
	v_mul_u32_u24_e32 v195, 0x1200, v198
	v_lshl_add_u32 v234, v199, 4, v195
	v_mul_u32_u24_e32 v195, 0x90, v198
	v_lshl_add_u32 v195, v199, 4, v195
	v_add_u32_e32 v236, 0x12c00, v195
	v_mul_u32_u24_e32 v195, 0x190, v192
	v_lshl_add_u32 v237, v193, 4, v195
	v_mul_u32_u24_e32 v195, 0x90, v192
	v_lshl_add_u32 v195, v193, 3, v195
	v_add_u32_e32 v238, 0x12c00, v195
	global_load_dwordx4 v[204:207], v224, s[4:5]
	global_load_dwordx4 v[208:211], v225, s[4:5]
	global_load_dwordx4 v[212:215], v226, s[4:5]
	global_load_dwordx4 v[216:219], v233, s[8:9]
	global_load_dwordx4 v[220:223], v234, s[8:9]
	v_add_u32_e32 v224, v224, v227
	v_add_u32_e32 v225, v225, v228
	v_add_u32_e32 v226, v226, v229
	s_add_u32 s8, s8, 0x80
	s_addc_u32 s9, s9, 0
	v_mov_b32_e32 v48, 0
	v_mov_b32_e32 v49, 0
	v_mov_b32_e32 v50, 0
	v_mov_b32_e32 v51, 0
	v_mov_b32_e32 v52, 0
	v_mov_b32_e32 v53, 0
	v_mov_b32_e32 v54, 0
	v_mov_b32_e32 v55, 0
	v_mov_b32_e32 v56, 0
	v_mov_b32_e32 v57, 0
	v_mov_b32_e32 v58, 0
	v_mov_b32_e32 v59, 0
	v_mov_b32_e32 v60, 0
	v_mov_b32_e32 v61, 0
	v_mov_b32_e32 v62, 0
	v_mov_b32_e32 v63, 0
	v_mov_b32_e32 v64, 0
	v_mov_b32_e32 v65, 0
	v_mov_b32_e32 v66, 0
	v_mov_b32_e32 v67, 0
	v_mov_b32_e32 v68, 0
	v_mov_b32_e32 v69, 0
	v_mov_b32_e32 v70, 0
	v_mov_b32_e32 v71, 0
	v_mov_b32_e32 v72, 0
	v_mov_b32_e32 v73, 0
	v_mov_b32_e32 v74, 0
	v_mov_b32_e32 v75, 0
	v_mov_b32_e32 v76, 0
	v_mov_b32_e32 v77, 0
	v_mov_b32_e32 v78, 0
	v_mov_b32_e32 v79, 0
	v_mov_b32_e32 v80, 0
	v_mov_b32_e32 v81, 0
	v_mov_b32_e32 v82, 0
	v_mov_b32_e32 v83, 0
	v_mov_b32_e32 v84, 0
	v_mov_b32_e32 v85, 0
	v_mov_b32_e32 v86, 0
	v_mov_b32_e32 v87, 0
	v_mov_b32_e32 v88, 0
	v_mov_b32_e32 v89, 0
	v_mov_b32_e32 v90, 0
	v_mov_b32_e32 v91, 0
	v_mov_b32_e32 v92, 0
	v_mov_b32_e32 v93, 0
	v_mov_b32_e32 v94, 0
	v_mov_b32_e32 v95, 0
	v_mov_b32_e32 v96, 0
	v_mov_b32_e32 v97, 0
	v_mov_b32_e32 v98, 0
	v_mov_b32_e32 v99, 0
	v_mov_b32_e32 v100, 0
	v_mov_b32_e32 v101, 0
	v_mov_b32_e32 v102, 0
	v_mov_b32_e32 v103, 0
	v_mov_b32_e32 v104, 0
	v_mov_b32_e32 v105, 0
	v_mov_b32_e32 v106, 0
	v_mov_b32_e32 v107, 0
	v_mov_b32_e32 v108, 0
	v_mov_b32_e32 v109, 0
	v_mov_b32_e32 v110, 0
	v_mov_b32_e32 v111, 0
	v_mov_b32_e32 v242, 0xf149f2ca
	v_mov_b32_e32 v244, 0
	v_mov_b32_e32 v243, 0xf149f2ca
	v_mov_b32_e32 v245, 0
	s_waitcnt vmcnt(0)
	v_lshl_add_u32 v195, v194, 5, v192
	v_lshlrev_b32_e32 v195, 12, v195
	v_lshl_add_u32 v250, v193, 3, v195
	v_add_u32_e32 v251, 0x10000, v250
	ds_write_b128 v230, v[204:207]
	ds_write_b128 v231, v[208:211]
	ds_write_b128 v232, v[212:215]
	ds_write_b128 v235, v[216:219]
	ds_write_b128 v236, v[220:223]
	s_waitcnt lgkmcnt(0)
	global_load_dwordx4 v[204:207], v224, s[4:5]
	global_load_dwordx4 v[208:211], v225, s[4:5]
	global_load_dwordx4 v[212:215], v226, s[4:5]
	global_load_dwordx4 v[216:219], v233, s[8:9]
	global_load_dwordx4 v[220:223], v234, s[8:9]
	s_barrier
; template <int DK>
; DI void dense_attn_item(LAS unsigned char* lds, const bf16_t* Qb, int ldq, const bf16_t* Kb, int ldk, const bf16_t* Kpe, const bf16_t* Vt, int nkeys, float sl2, bf16_t* Ob) {
;     ...
;     for (int kt = 0; kt < ntiles; ++kt) {
;         const int cur = kt & 1;
;         if (kt + 1 < ntiles) DA_LOAD((kt + 1) * 64);
;         const LAS unsigned char* kb_ = lds + cur * KTILE; const LAS unsigned char* vb_ = lds + 2 * KTILE + cur * VTILE;
; #pragma unroll
;         for (int kc = 0; kc < 2; ++kc) {
;             f32x4 sacc[2][2];
; #pragma unroll
;             for (int kb = 0; kb < 2; ++kb) {
;                 sacc[0][kb] = (f32x4){0.f, 0.f, 0.f, 0.f}; sacc[1][kb] = (f32x4){0.f, 0.f, 0.f, 0.f};
; #pragma unroll
;                 for (int kh = 0; kh < KS / 2; ++kh) {
;                     const bf16x8 k0 = *(const LAS bf16x8*)(kb_ + ((2 * kc + kb) * 16 + r16) * KROW + (2 * kh) * 64 + q4 * 16);
;                     const bf16x8 k1 = *(const LAS bf16x8*)(kb_ + ((2 * kc + kb) * 16 + r16) * KROW + (2 * kh + 1) * 64 + q4 * 16);
;                     __builtin_amdgcn_s_setprio(1);
;                     sacc[0][kb] = MFMA16(k0, qf[0][2 * kh], sacc[0][kb]); sacc[1][kb] = MFMA16(k0, qf[1][2 * kh], sacc[1][kb]);
;                     sacc[0][kb] = MFMA16(k1, qf[0][2 * kh + 1], sacc[0][kb]); sacc[1][kb] = MFMA16(k1, qf[1][2 * kh + 1], sacc[1][kb]);
;                     __builtin_amdgcn_s_setprio(0);
;                 }
;             }
;             bf16x8 pb[2];
; #pragma unroll
;             for (int qg = 0; qg < 2; ++qg) {
;                 float mx = fmaxf(fmaxf(fmaxf(sacc[qg][0][0], sacc[qg][0][1]), fmaxf(sacc[qg][0][2], sacc[qg][0][3])), fmaxf(fmaxf(sacc[qg][1][0], sacc[qg][1][1]), fmaxf(sacc[qg][1][2], sacc[qg][1][3])));
;                 mx = fmaxf(mx, __shfl_xor(mx, 16)); mx = fmaxf(mx, __shfl_xor(mx, 32));
;                 const float mnew = fmaxf(mrun[qg], mx * sl2), alpha = fast_exp2(mrun[qg] - mnew);
;                 mrun[qg] = mnew;
;                 float ps = 0.f;
; #pragma unroll
;                 for (int kb = 0; kb < 2; ++kb)
; #pragma unroll
;                     for (int j = 0; j < 4; ++j) { const float pv = fast_exp2(sacc[qg][kb][j] * sl2 - mnew); sacc[qg][kb][j] = pv; ps += pv; }
;                 lsum[qg] = lsum[qg] * alpha + ps;
; #pragma unroll
;                 for (int d = 0; d < 8; ++d) oacc[qg][d] *= alpha;
	v_mov_b32_e32 v239, v237
	ds_read_b128 v[144:147], v239 offset:0
	ds_read_b128 v[148:151], v239 offset:64
	ds_read_b128 v[152:155], v239 offset:128
	ds_read_b128 v[156:159], v239 offset:192
	ds_read_b128 v[160:163], v239 offset:256
	ds_read_b128 v[164:167], v239 offset:320
	s_waitcnt lgkmcnt(5)
	v_mfma_f32_16x16x32_bf16 v[112:115], v[144:147], v[0:3], 0
	v_mfma_f32_16x16x32_bf16 v[120:123], v[144:147], v[24:27], 0
	s_waitcnt lgkmcnt(4)
	v_mfma_f32_16x16x32_bf16 v[112:115], v[148:151], v[4:7], v[112:115]
	v_mfma_f32_16x16x32_bf16 v[120:123], v[148:151], v[28:31], v[120:123]
	s_waitcnt lgkmcnt(3)
	v_mfma_f32_16x16x32_bf16 v[112:115], v[152:155], v[8:11], v[112:115]
	v_mfma_f32_16x16x32_bf16 v[120:123], v[152:155], v[32:35], v[120:123]
	s_waitcnt lgkmcnt(2)
	v_mfma_f32_16x16x32_bf16 v[112:115], v[156:159], v[12:15], v[112:115]
	v_mfma_f32_16x16x32_bf16 v[120:123], v[156:159], v[36:39], v[120:123]
	s_waitcnt lgkmcnt(1)
	v_mfma_f32_16x16x32_bf16 v[112:115], v[160:163], v[16:19], v[112:115]
	v_mfma_f32_16x16x32_bf16 v[120:123], v[160:163], v[40:43], v[120:123]
	s_waitcnt lgkmcnt(0)
	v_mfma_f32_16x16x32_bf16 v[112:115], v[164:167], v[20:23], v[112:115]
	v_mfma_f32_16x16x32_bf16 v[120:123], v[164:167], v[44:47], v[120:123]
	ds_read_b128 v[144:147], v239 offset:6400
	ds_read_b128 v[148:151], v239 offset:6464
	ds_read_b128 v[152:155], v239 offset:6528
	ds_read_b128 v[156:159], v239 offset:6592
	ds_read_b128 v[160:163], v239 offset:6656
	ds_read_b128 v[164:167], v239 offset:6720
	s_waitcnt lgkmcnt(5)
	v_mfma_f32_16x16x32_bf16 v[116:119], v[144:147], v[0:3], 0
	v_mfma_f32_16x16x32_bf16 v[124:127], v[144:147], v[24:27], 0
	s_waitcnt lgkmcnt(4)
	v_mfma_f32_16x16x32_bf16 v[116:119], v[148:151], v[4:7], v[116:119]
	v_mfma_f32_16x16x32_bf16 v[124:127], v[148:151], v[28:31], v[124:127]
	s_waitcnt lgkmcnt(3)
	v_mfma_f32_16x16x32_bf16 v[116:119], v[152:155], v[8:11], v[116:119]
	v_mfma_f32_16x16x32_bf16 v[124:127], v[152:155], v[32:35], v[124:127]
	s_waitcnt lgkmcnt(2)
	v_mfma_f32_16x16x32_bf16 v[116:119], v[156:159], v[12:15], v[116:119]
	v_mfma_f32_16x16x32_bf16 v[124:127], v[156:159], v[36:39], v[124:127]
	s_waitcnt lgkmcnt(1)
	v_mfma_f32_16x16x32_bf16 v[116:119], v[160:163], v[16:19], v[116:119]
	v_mfma_f32_16x16x32_bf16 v[124:127], v[160:163], v[40:43], v[124:127]
	s_waitcnt lgkmcnt(0)
	v_mfma_f32_16x16x32_bf16 v[116:119], v[164:167], v[20:23], v[116:119]
	v_mfma_f32_16x16x32_bf16 v[124:127], v[164:167], v[44:47], v[124:127]
	s_mov_b32 s23, 0
	s_mov_b32 s27, 0
dn1_top:
	s_add_u32 s57, s27, 1
	s_cmp_eq_u32 s57, 3
	s_cselect_b32 s57, 0, s57
	s_mul_i32 s36, s27, 0x6400
	s_mul_i32 s54, s27, 0x4800
	s_mul_i32 s37, s57, 0x6400
	s_mul_i32 s56, s57, 0x4800
	v_add_u32_e32 v239, s36, v237
	v_add_u32_e32 v240, s37, v237
	v_add_u32_e32 v241, s54, v238
	v_add_u32_e32 v196, s37, v230
	v_add_u32_e32 v197, s37, v231
	v_add_u32_e32 v198, s37, v232
	v_add_u32_e32 v199, s56, v235
	v_add_u32_e32 v200, s56, v236
	v_add_u32_e32 v224, v224, v227
	v_add_u32_e32 v225, v225, v228
	v_add_u32_e32 v226, v226, v229
	s_add_u32 s8, s8, 0x80
	s_addc_u32 s9, s9, 0
	s_waitcnt vmcnt(0)
	ds_write_b128 v196, v[204:207]
	ds_write_b128 v197, v[208:211]
	ds_write_b128 v198, v[212:215]
	ds_write_b128 v199, v[216:219]
	ds_write_b128 v200, v[220:223]
	ds_read_b128 v[144:147], v239 offset:12800
	ds_read_b128 v[148:151], v239 offset:12864
	ds_read_b128 v[152:155], v239 offset:12928
	ds_read_b128 v[156:159], v239 offset:12992
	ds_read_b128 v[160:163], v239 offset:13056
	ds_read_b128 v[164:167], v239 offset:13120
	v_max3_f32 v193, v112, v113, v114
	v_max3_f32 v195, v120, v121, v122
	v_max3_f32 v192, v115, v116, v117
	v_max3_f32 v194, v123, v124, v125
	v_max3_f32 v193, v193, v118, v119
	v_max3_f32 v195, v195, v126, v127
	v_max_f32_e32 v193, v193, v192
	v_max_f32_e32 v195, v195, v194
	v_mov_b32_e32 v192, v193
	v_mov_b32_e32 v194, v195
	s_nop 1
	v_permlane16_swap_b32_e32 v193, v192
	s_waitcnt lgkmcnt(5)
	global_load_dwordx4 v[204:207], v224, s[4:5]
	global_load_dwordx4 v[208:211], v225, s[4:5]
	global_load_dwordx4 v[212:215], v226, s[4:5]
	global_load_dwordx4 v[216:219], v233, s[8:9]
	global_load_dwordx4 v[220:223], v234, s[8:9]
	v_mfma_f32_16x16x32_bf16 v[128:131], v[144:147], v[0:3], 0
	v_permlane16_swap_b32_e32 v195, v194
	v_max_f32_e32 v193, v193, v192
	v_max_f32_e32 v195, v195, v194
	v_mfma_f32_16x16x32_bf16 v[136:139], v[144:147], v[24:27], 0
	v_mov_b32_e32 v192, v193
	v_mov_b32_e32 v194, v195
	s_nop 1
	ds_read_b128 v[144:147], v239 offset:19200
	s_waitcnt lgkmcnt(5)
	v_mfma_f32_16x16x32_bf16 v[128:131], v[148:151], v[4:7], v[128:131]
	v_permlane32_swap_b32_e32 v193, v192
	v_permlane32_swap_b32_e32 v195, v194
	v_max_f32_e32 v193, v193, v192
	v_mfma_f32_16x16x32_bf16 v[136:139], v[148:151], v[28:31], v[136:139]
	v_max_f32_e32 v195, v195, v194
	v_mul_f32_e32 v193, s22, v193
	v_mul_f32_e32 v195, s22, v195
	ds_read_b128 v[148:151], v239 offset:19264
	s_waitcnt lgkmcnt(5)
	v_mfma_f32_16x16x32_bf16 v[128:131], v[152:155], v[8:11], v[128:131]
	v_max_f32_e32 v192, v242, v193
	v_max_f32_e32 v194, v243, v195
	v_sub_f32_e32 v193, v192, v242
	v_mfma_f32_16x16x32_bf16 v[136:139], v[152:155], v[32:35], v[136:139]
	v_sub_f32_e32 v195, v194, v243
	v_cmp_gt_f32_e64 s[68:69], v193, s29
	v_cmp_gt_f32_e64 s[0:1], v195, s29
	ds_read_b128 v[152:155], v239 offset:19328
	s_waitcnt lgkmcnt(5)
	v_mfma_f32_16x16x32_bf16 v[128:131], v[156:159], v[12:15], v[128:131]
	s_cmp_lg_u64 s[68:69], 0
	s_cselect_b64 s[68:69], -1, 0
	s_cmp_lg_u64 s[0:1], 0
	v_mfma_f32_16x16x32_bf16 v[136:139], v[156:159], v[36:39], v[136:139]
	s_cselect_b64 s[0:1], -1, 0
	v_cndmask_b32_e64 v192, v242, v192, s[68:69]
	v_cndmask_b32_e64 v194, v243, v194, s[0:1]
	ds_read_b128 v[156:159], v239 offset:19392
	s_waitcnt lgkmcnt(5)
; #define LAS __attribute__((address_space(3)))
; template <int DK>
; DI void dense_attn_item(LAS unsigned char* lds, const bf16_t* Qb, int ldq, const bf16_t* Kb, int ldk, const bf16_t* Kpe, const bf16_t* Vt, int nkeys, float sl2, bf16_t* Ob) {
;     ...
; #pragma unroll
;             for (int qg = 0; qg < 2; ++qg) {
;                 float mx = fmaxf(fmaxf(fmaxf(sacc[qg][0][0], sacc[qg][0][1]), fmaxf(sacc[qg][0][2], sacc[qg][0][3])), fmaxf(fmaxf(sacc[qg][1][0], sacc[qg][1][1]), fmaxf(sacc[qg][1][2], sacc[qg][1][3])));
;                 mx = fmaxf(mx, __shfl_xor(mx, 16)); mx = fmaxf(mx, __shfl_xor(mx, 32));
;                 const float mnew = fmaxf(mrun[qg], mx * sl2), alpha = fast_exp2(mrun[qg] - mnew);
;                 mrun[qg] = mnew;
;                 float ps = 0.f;
; #pragma unroll
;                 for (int kb = 0; kb < 2; ++kb)
; #pragma unroll
;                     for (int j = 0; j < 4; ++j) { const float pv = fast_exp2(sacc[qg][kb][j] * sl2 - mnew); sacc[qg][kb][j] = pv; ps += pv; }
;                 lsum[qg] = lsum[qg] * alpha + ps;
; #pragma unroll
;                 for (int d = 0; d < 8; ++d) oacc[qg][d] *= alpha;
;                 u32x4 w; w.x = cvt_pk_bf16(sacc[qg][0][0], sacc[qg][0][1]); w.y = cvt_pk_bf16(sacc[qg][0][2], sacc[qg][0][3]);
;                 w.z = cvt_pk_bf16(sacc[qg][1][0], sacc[qg][1][1]); w.w = cvt_pk_bf16(sacc[qg][1][2], sacc[qg][1][3]);
;                 pb[qg] = __builtin_bit_cast(bf16x8, w);
;             }
; #pragma unroll
;             for (int dh = 0; dh < 4; ++dh) {
;                 bf16x8 vfr[2];
; #pragma unroll
;                 for (int d4 = 0; d4 < 2; ++d4) {
;                     const int d = dh * 2 + d4;
;                     const u32x2 lo = *(const LAS u32x2*)(vb_ + (d * 16 + r16) * VROW + (kc * 32 + q4 * 4) * 2);
;                     const u32x2 hi = *(const LAS u32x2*)(vb_ + (d * 16 + r16) * VROW + (kc * 32 + 16 + q4 * 4) * 2);
;                     u32x4 w; w.x = lo.x; w.y = lo.y; w.z = hi.x; w.w = hi.y;
;                     vfr[d4] = __builtin_bit_cast(bf16x8, w);
;                 }
;                 __builtin_amdgcn_s_setprio(1);
; #pragma unroll
;                 for (int d4 = 0; d4 < 2; ++d4) { const int d = dh * 2 + d4; oacc[0][d] = MFMA16(vfr[d4], pb[0], oacc[0][d]); oacc[1][d] = MFMA16(vfr[d4], pb[1], oacc[1][d]); }
;                 __builtin_amdgcn_s_setprio(0);
;             }
	v_mfma_f32_16x16x32_bf16 v[128:131], v[160:163], v[16:19], v[128:131]
	v_sub_f32_e32 v193, v242, v192
	v_sub_f32_e32 v195, v243, v194
	v_exp_f32_e32 v246, v193
	v_mfma_f32_16x16x32_bf16 v[136:139], v[160:163], v[40:43], v[136:139]
	v_exp_f32_e32 v248, v195
	v_mov_b32_e32 v242, v192
	v_mov_b32_e32 v243, v194
	ds_read_b128 v[160:163], v239 offset:19456
	s_waitcnt lgkmcnt(5)
	v_mfma_f32_16x16x32_bf16 v[128:131], v[164:167], v[20:23], v[128:131]
	v_pk_fma_f32 v[112:113], v[112:113], v[254:255], v[192:193] op_sel_hi:[1,0,0] neg_lo:[0,0,1] neg_hi:[0,0,1]
	v_pk_fma_f32 v[120:121], v[120:121], v[254:255], v[194:195] op_sel_hi:[1,0,0] neg_lo:[0,0,1] neg_hi:[0,0,1]
	v_pk_fma_f32 v[114:115], v[114:115], v[254:255], v[192:193] op_sel_hi:[1,0,0] neg_lo:[0,0,1] neg_hi:[0,0,1]
	v_mfma_f32_16x16x32_bf16 v[136:139], v[164:167], v[44:47], v[136:139]
	v_pk_fma_f32 v[122:123], v[122:123], v[254:255], v[194:195] op_sel_hi:[1,0,0] neg_lo:[0,0,1] neg_hi:[0,0,1]
	v_pk_fma_f32 v[116:117], v[116:117], v[254:255], v[192:193] op_sel_hi:[1,0,0] neg_lo:[0,0,1] neg_hi:[0,0,1]
	v_pk_fma_f32 v[124:125], v[124:125], v[254:255], v[194:195] op_sel_hi:[1,0,0] neg_lo:[0,0,1] neg_hi:[0,0,1]
	ds_read_b128 v[164:167], v239 offset:19520
	s_waitcnt lgkmcnt(5)
	v_mfma_f32_16x16x32_bf16 v[132:135], v[144:147], v[0:3], 0
	v_pk_fma_f32 v[118:119], v[118:119], v[254:255], v[192:193] op_sel_hi:[1,0,0] neg_lo:[0,0,1] neg_hi:[0,0,1]
	v_pk_fma_f32 v[126:127], v[126:127], v[254:255], v[194:195] op_sel_hi:[1,0,0] neg_lo:[0,0,1] neg_hi:[0,0,1]
	v_exp_f32_e32 v112, v112
	v_mfma_f32_16x16x32_bf16 v[140:143], v[144:147], v[24:27], 0
	v_exp_f32_e32 v120, v120
	v_exp_f32_e32 v113, v113
	v_exp_f32_e32 v121, v121
	ds_read_b64 v[168:169], v241 offset:0
	ds_read_b64 v[170:171], v241 offset:32
	s_waitcnt lgkmcnt(6)
	v_mfma_f32_16x16x32_bf16 v[132:135], v[148:151], v[4:7], v[132:135]
	v_exp_f32_e32 v114, v114
	v_exp_f32_e32 v122, v122
	v_exp_f32_e32 v115, v115
	v_mfma_f32_16x16x32_bf16 v[140:143], v[148:151], v[28:31], v[140:143]
	v_exp_f32_e32 v123, v123
	v_exp_f32_e32 v116, v116
	v_exp_f32_e32 v124, v124
	ds_read_b64 v[172:173], v241 offset:2304
	ds_read_b64 v[174:175], v241 offset:2336
	s_waitcnt lgkmcnt(7)
	v_mfma_f32_16x16x32_bf16 v[132:135], v[152:155], v[8:11], v[132:135]
	v_exp_f32_e32 v117, v117
	v_exp_f32_e32 v125, v125
	v_exp_f32_e32 v118, v118
	v_mfma_f32_16x16x32_bf16 v[140:143], v[152:155], v[32:35], v[140:143]
	v_exp_f32_e32 v126, v126
	v_exp_f32_e32 v119, v119
	v_exp_f32_e32 v127, v127
	ds_read_b64 v[176:177], v241 offset:4608
	ds_read_b64 v[178:179], v241 offset:4640
	s_waitcnt lgkmcnt(8)
	v_mfma_f32_16x16x32_bf16 v[132:135], v[156:159], v[12:15], v[132:135]
	v_pk_add_f32 v[196:197], v[112:113], v[114:115]
	v_pk_add_f32 v[198:199], v[120:121], v[122:123]
	v_pk_add_f32 v[196:197], v[196:197], v[116:117]
	v_mfma_f32_16x16x32_bf16 v[140:143], v[156:159], v[36:39], v[140:143]
	v_pk_add_f32 v[198:199], v[198:199], v[124:125]
	v_pk_add_f32 v[196:197], v[196:197], v[118:119]
	v_pk_add_f32 v[198:199], v[198:199], v[126:127]
	ds_read_b64 v[180:181], v241 offset:6912
	ds_read_b64 v[182:183], v241 offset:6944
	s_waitcnt lgkmcnt(9)
	v_mfma_f32_16x16x32_bf16 v[132:135], v[160:163], v[16:19], v[132:135]
	v_add_f32_e32 v193, v196, v197
	v_add_f32_e32 v195, v198, v199
	v_fma_f32 v244, v244, v246, v193
	v_mfma_f32_16x16x32_bf16 v[140:143], v[160:163], v[40:43], v[140:143]
	v_fma_f32 v245, v245, v248, v195
	v_cvt_pk_bf16_f32 v184, v112, v113
	v_cvt_pk_bf16_f32 v188, v120, v121
	s_waitcnt lgkmcnt(8)
	v_mfma_f32_16x16x32_bf16 v[132:135], v[164:167], v[20:23], v[132:135]
	v_cvt_pk_bf16_f32 v185, v114, v115
	v_cvt_pk_bf16_f32 v189, v122, v123
	v_cvt_pk_bf16_f32 v186, v116, v117
	v_mfma_f32_16x16x32_bf16 v[140:143], v[164:167], v[44:47], v[140:143]
	v_cvt_pk_bf16_f32 v190, v124, v125
	v_cvt_pk_bf16_f32 v187, v118, v119
	v_cvt_pk_bf16_f32 v191, v126, v127
	s_or_b64 vcc, s[68:69], s[0:1]
	s_cbranch_vccz dn1_nr1
	v_pk_mul_f32 v[48:49], v[48:49], v[246:247] op_sel_hi:[1,0]
	v_pk_mul_f32 v[50:51], v[50:51], v[246:247] op_sel_hi:[1,0]
	v_pk_mul_f32 v[80:81], v[80:81], v[248:249] op_sel_hi:[1,0]
	v_pk_mul_f32 v[82:83], v[82:83], v[248:249] op_sel_hi:[1,0]
	s_waitcnt lgkmcnt(6)
	v_mfma_f32_16x16x32_bf16 v[48:51], v[168:171], v[184:187], v[48:51]
	v_pk_mul_f32 v[52:53], v[52:53], v[246:247] op_sel_hi:[1,0]
	v_pk_mul_f32 v[54:55], v[54:55], v[246:247] op_sel_hi:[1,0]
	v_mfma_f32_16x16x32_bf16 v[80:83], v[168:171], v[188:191], v[80:83]
	v_pk_mul_f32 v[84:85], v[84:85], v[248:249] op_sel_hi:[1,0]
	v_pk_mul_f32 v[86:87], v[86:87], v[248:249] op_sel_hi:[1,0]
	ds_read_b64 v[168:169], v241 offset:9216
	ds_read_b64 v[170:171], v241 offset:9248
	s_waitcnt lgkmcnt(6)
	v_mfma_f32_16x16x32_bf16 v[52:55], v[172:175], v[184:187], v[52:55]
	v_pk_mul_f32 v[56:57], v[56:57], v[246:247] op_sel_hi:[1,0]
	v_pk_mul_f32 v[58:59], v[58:59], v[246:247] op_sel_hi:[1,0]
	v_mfma_f32_16x16x32_bf16 v[84:87], v[172:175], v[188:191], v[84:87]
	v_pk_mul_f32 v[88:89], v[88:89], v[248:249] op_sel_hi:[1,0]
	v_pk_mul_f32 v[90:91], v[90:91], v[248:249] op_sel_hi:[1,0]
	ds_read_b64 v[172:173], v241 offset:11520
	ds_read_b64 v[174:175], v241 offset:11552
	s_waitcnt lgkmcnt(6)
	v_mfma_f32_16x16x32_bf16 v[56:59], v[176:179], v[184:187], v[56:59]
	v_pk_mul_f32 v[60:61], v[60:61], v[246:247] op_sel_hi:[1,0]
	v_pk_mul_f32 v[62:63], v[62:63], v[246:247] op_sel_hi:[1,0]
	v_mfma_f32_16x16x32_bf16 v[88:91], v[176:179], v[188:191], v[88:91]
	v_pk_mul_f32 v[92:93], v[92:93], v[248:249] op_sel_hi:[1,0]
	v_pk_mul_f32 v[94:95], v[94:95], v[248:249] op_sel_hi:[1,0]
	ds_read_b64 v[176:177], v241 offset:13824
	ds_read_b64 v[178:179], v241 offset:13856
	s_waitcnt lgkmcnt(6)
; template <int DK>
; DI void dense_attn_item(LAS unsigned char* lds, const bf16_t* Qb, int ldq, const bf16_t* Kb, int ldk, const bf16_t* Kpe, const bf16_t* Vt, int nkeys, float sl2, bf16_t* Ob) {
;     ...
;     for (int kt = 0; kt < ntiles; ++kt) {
;         const int cur = kt & 1;
;         if (kt + 1 < ntiles) DA_LOAD((kt + 1) * 64);
;         const LAS unsigned char* kb_ = lds + cur * KTILE; const LAS unsigned char* vb_ = lds + 2 * KTILE + cur * VTILE;
; #pragma unroll
;         for (int kc = 0; kc < 2; ++kc) {
;             f32x4 sacc[2][2];
; #pragma unroll
;             for (int kb = 0; kb < 2; ++kb) {
;                 sacc[0][kb] = (f32x4){0.f, 0.f, 0.f, 0.f}; sacc[1][kb] = (f32x4){0.f, 0.f, 0.f, 0.f};
; #pragma unroll
;                 for (int kh = 0; kh < KS / 2; ++kh) {
;                     const bf16x8 k0 = *(const LAS bf16x8*)(kb_ + ((2 * kc + kb) * 16 + r16) * KROW + (2 * kh) * 64 + q4 * 16);
;                     const bf16x8 k1 = *(const LAS bf16x8*)(kb_ + ((2 * kc + kb) * 16 + r16) * KROW + (2 * kh + 1) * 64 + q4 * 16);
;                     __builtin_amdgcn_s_setprio(1);
;                     sacc[0][kb] = MFMA16(k0, qf[0][2 * kh], sacc[0][kb]); sacc[1][kb] = MFMA16(k0, qf[1][2 * kh], sacc[1][kb]);
;                     sacc[0][kb] = MFMA16(k1, qf[0][2 * kh + 1], sacc[0][kb]); sacc[1][kb] = MFMA16(k1, qf[1][2 * kh + 1], sacc[1][kb]);
;                     __builtin_amdgcn_s_setprio(0);
;                 }
;             }
;             bf16x8 pb[2];
; #pragma unroll
;             for (int qg = 0; qg < 2; ++qg) {
;                 float mx = fmaxf(fmaxf(fmaxf(sacc[qg][0][0], sacc[qg][0][1]), fmaxf(sacc[qg][0][2], sacc[qg][0][3])), fmaxf(fmaxf(sacc[qg][1][0], sacc[qg][1][1]), fmaxf(sacc[qg][1][2], sacc[qg][1][3])));
;                 mx = fmaxf(mx, __shfl_xor(mx, 16)); mx = fmaxf(mx, __shfl_xor(mx, 32));
;                 const float mnew = fmaxf(mrun[qg], mx * sl2), alpha = fast_exp2(mrun[qg] - mnew);
;                 mrun[qg] = mnew;
;                 float ps = 0.f;
; #pragma unroll
;                 for (int kb = 0; kb < 2; ++kb)
; #pragma unroll
;                     for (int j = 0; j < 4; ++j) { const float pv = fast_exp2(sacc[qg][kb][j] * sl2 - mnew); sacc[qg][kb][j] = pv; ps += pv; }
;                 lsum[qg] = lsum[qg] * alpha + ps;
; #pragma unroll
;                 for (int d = 0; d < 8; ++d) oacc[qg][d] *= alpha;
	v_mfma_f32_16x16x32_bf16 v[60:63], v[180:183], v[184:187], v[60:63]
	v_pk_mul_f32 v[64:65], v[64:65], v[246:247] op_sel_hi:[1,0]
	v_pk_mul_f32 v[66:67], v[66:67], v[246:247] op_sel_hi:[1,0]
	v_mfma_f32_16x16x32_bf16 v[92:95], v[180:183], v[188:191], v[92:95]
	v_pk_mul_f32 v[96:97], v[96:97], v[248:249] op_sel_hi:[1,0]
	v_pk_mul_f32 v[98:99], v[98:99], v[248:249] op_sel_hi:[1,0]
	ds_read_b64 v[180:181], v241 offset:16128
	ds_read_b64 v[182:183], v241 offset:16160
	s_waitcnt lgkmcnt(6)
	v_mfma_f32_16x16x32_bf16 v[64:67], v[168:171], v[184:187], v[64:67]
	v_pk_mul_f32 v[68:69], v[68:69], v[246:247] op_sel_hi:[1,0]
	v_pk_mul_f32 v[70:71], v[70:71], v[246:247] op_sel_hi:[1,0]
	v_mfma_f32_16x16x32_bf16 v[96:99], v[168:171], v[188:191], v[96:99]
	v_pk_mul_f32 v[100:101], v[100:101], v[248:249] op_sel_hi:[1,0]
	v_pk_mul_f32 v[102:103], v[102:103], v[248:249] op_sel_hi:[1,0]
	s_waitcnt lgkmcnt(4)
	v_mfma_f32_16x16x32_bf16 v[68:71], v[172:175], v[184:187], v[68:71]
	v_pk_mul_f32 v[72:73], v[72:73], v[246:247] op_sel_hi:[1,0]
	v_pk_mul_f32 v[74:75], v[74:75], v[246:247] op_sel_hi:[1,0]
	v_mfma_f32_16x16x32_bf16 v[100:103], v[172:175], v[188:191], v[100:103]
	v_pk_mul_f32 v[104:105], v[104:105], v[248:249] op_sel_hi:[1,0]
	v_pk_mul_f32 v[106:107], v[106:107], v[248:249] op_sel_hi:[1,0]
	s_waitcnt lgkmcnt(2)
	v_mfma_f32_16x16x32_bf16 v[72:75], v[176:179], v[184:187], v[72:75]
	v_pk_mul_f32 v[76:77], v[76:77], v[246:247] op_sel_hi:[1,0]
	v_pk_mul_f32 v[78:79], v[78:79], v[246:247] op_sel_hi:[1,0]
	v_mfma_f32_16x16x32_bf16 v[104:107], v[176:179], v[188:191], v[104:107]
	v_pk_mul_f32 v[108:109], v[108:109], v[248:249] op_sel_hi:[1,0]
	v_pk_mul_f32 v[110:111], v[110:111], v[248:249] op_sel_hi:[1,0]
	s_waitcnt lgkmcnt(0)
	v_mfma_f32_16x16x32_bf16 v[76:79], v[180:183], v[184:187], v[76:79]
	v_mfma_f32_16x16x32_bf16 v[108:111], v[180:183], v[188:191], v[108:111]
	s_branch dn1_jn1
dn1_nr1:
	s_nop 1
	s_waitcnt lgkmcnt(6)
	v_mfma_f32_16x16x32_bf16 v[48:51], v[168:171], v[184:187], v[48:51]
	v_mfma_f32_16x16x32_bf16 v[80:83], v[168:171], v[188:191], v[80:83]
	ds_read_b64 v[168:169], v241 offset:9216
	ds_read_b64 v[170:171], v241 offset:9248
	s_waitcnt lgkmcnt(6)
	v_mfma_f32_16x16x32_bf16 v[52:55], v[172:175], v[184:187], v[52:55]
	v_mfma_f32_16x16x32_bf16 v[84:87], v[172:175], v[188:191], v[84:87]
	ds_read_b64 v[172:173], v241 offset:11520
	ds_read_b64 v[174:175], v241 offset:11552
	s_waitcnt lgkmcnt(6)
	v_mfma_f32_16x16x32_bf16 v[56:59], v[176:179], v[184:187], v[56:59]
	v_mfma_f32_16x16x32_bf16 v[88:91], v[176:179], v[188:191], v[88:91]
	ds_read_b64 v[176:177], v241 offset:13824
	ds_read_b64 v[178:179], v241 offset:13856
	s_waitcnt lgkmcnt(6)
	v_mfma_f32_16x16x32_bf16 v[60:63], v[180:183], v[184:187], v[60:63]
	v_mfma_f32_16x16x32_bf16 v[92:95], v[180:183], v[188:191], v[92:95]
	ds_read_b64 v[180:181], v241 offset:16128
	ds_read_b64 v[182:183], v241 offset:16160
	s_waitcnt lgkmcnt(6)
	v_mfma_f32_16x16x32_bf16 v[64:67], v[168:171], v[184:187], v[64:67]
	v_mfma_f32_16x16x32_bf16 v[96:99], v[168:171], v[188:191], v[96:99]
	s_waitcnt lgkmcnt(4)
	v_mfma_f32_16x16x32_bf16 v[68:71], v[172:175], v[184:187], v[68:71]
	v_mfma_f32_16x16x32_bf16 v[100:103], v[172:175], v[188:191], v[100:103]
	s_waitcnt lgkmcnt(2)
	v_mfma_f32_16x16x32_bf16 v[72:75], v[176:179], v[184:187], v[72:75]
	v_mfma_f32_16x16x32_bf16 v[104:107], v[176:179], v[188:191], v[104:107]
	s_waitcnt lgkmcnt(0)
	v_mfma_f32_16x16x32_bf16 v[76:79], v[180:183], v[184:187], v[76:79]
	v_mfma_f32_16x16x32_bf16 v[108:111], v[180:183], v[188:191], v[108:111]
dn1_jn1:
	s_waitcnt lgkmcnt(0)
	s_barrier
	ds_read_b128 v[144:147], v240 offset:0
	ds_read_b128 v[148:151], v240 offset:64
	ds_read_b128 v[152:155], v240 offset:128
	ds_read_b128 v[156:159], v240 offset:192
	ds_read_b128 v[160:163], v240 offset:256
	ds_read_b128 v[164:167], v240 offset:320
	v_max3_f32 v193, v128, v129, v130
	v_max3_f32 v195, v136, v137, v138
	v_max3_f32 v192, v131, v132, v133
	v_max3_f32 v194, v139, v140, v141
	v_max3_f32 v193, v193, v134, v135
	v_max3_f32 v195, v195, v142, v143
	v_max_f32_e32 v193, v193, v192
	v_max_f32_e32 v195, v195, v194
	v_mov_b32_e32 v192, v193
	v_mov_b32_e32 v194, v195
	s_nop 1
	v_permlane16_swap_b32_e32 v193, v192
	s_waitcnt lgkmcnt(5)
	v_mfma_f32_16x16x32_bf16 v[112:115], v[144:147], v[0:3], 0
	v_permlane16_swap_b32_e32 v195, v194
	v_max_f32_e32 v193, v193, v192
	v_max_f32_e32 v195, v195, v194
	v_mfma_f32_16x16x32_bf16 v[120:123], v[144:147], v[24:27], 0
	v_mov_b32_e32 v192, v193
	v_mov_b32_e32 v194, v195
	s_nop 1
	ds_read_b128 v[144:147], v240 offset:6400
	s_waitcnt lgkmcnt(5)
	v_mfma_f32_16x16x32_bf16 v[112:115], v[148:151], v[4:7], v[112:115]
	v_permlane32_swap_b32_e32 v193, v192
	v_permlane32_swap_b32_e32 v195, v194
	v_max_f32_e32 v193, v193, v192
	v_mfma_f32_16x16x32_bf16 v[120:123], v[148:151], v[28:31], v[120:123]
	v_max_f32_e32 v195, v195, v194
	v_mul_f32_e32 v193, s22, v193
	v_mul_f32_e32 v195, s22, v195
	ds_read_b128 v[148:151], v240 offset:6464
	s_waitcnt lgkmcnt(5)
	v_mfma_f32_16x16x32_bf16 v[112:115], v[152:155], v[8:11], v[112:115]
	v_max_f32_e32 v192, v242, v193
	v_max_f32_e32 v194, v243, v195
	v_sub_f32_e32 v193, v192, v242
	v_mfma_f32_16x16x32_bf16 v[120:123], v[152:155], v[32:35], v[120:123]
	v_sub_f32_e32 v195, v194, v243
	v_cmp_gt_f32_e64 s[68:69], v193, s29
	v_cmp_gt_f32_e64 s[0:1], v195, s29
	ds_read_b128 v[152:155], v240 offset:6528
	s_waitcnt lgkmcnt(5)
	v_mfma_f32_16x16x32_bf16 v[112:115], v[156:159], v[12:15], v[112:115]
	s_cmp_lg_u64 s[68:69], 0
	s_cselect_b64 s[68:69], -1, 0
	s_cmp_lg_u64 s[0:1], 0
	v_mfma_f32_16x16x32_bf16 v[120:123], v[156:159], v[36:39], v[120:123]
	s_cselect_b64 s[0:1], -1, 0
	v_cndmask_b32_e64 v192, v242, v192, s[68:69]
	v_cndmask_b32_e64 v194, v243, v194, s[0:1]
	ds_read_b128 v[156:159], v240 offset:6592
	s_waitcnt lgkmcnt(5)
; #define LAS __attribute__((address_space(3)))
; template <int DK>
; DI void dense_attn_item(LAS unsigned char* lds, const bf16_t* Qb, int ldq, const bf16_t* Kb, int ldk, const bf16_t* Kpe, const bf16_t* Vt, int nkeys, float sl2, bf16_t* Ob) {
;     ...
;             for (int qg = 0; qg < 2; ++qg) {
;                 float mx = fmaxf(fmaxf(fmaxf(sacc[qg][0][0], sacc[qg][0][1]), fmaxf(sacc[qg][0][2], sacc[qg][0][3])), fmaxf(fmaxf(sacc[qg][1][0], sacc[qg][1][1]), fmaxf(sacc[qg][1][2], sacc[qg][1][3])));
;                 mx = fmaxf(mx, __shfl_xor(mx, 16)); mx = fmaxf(mx, __shfl_xor(mx, 32));
;                 const float mnew = fmaxf(mrun[qg], mx * sl2), alpha = fast_exp2(mrun[qg] - mnew);
;                 mrun[qg] = mnew;
;                 float ps = 0.f;
; #pragma unroll
;                 for (int kb = 0; kb < 2; ++kb)
; #pragma unroll
;                     for (int j = 0; j < 4; ++j) { const float pv = fast_exp2(sacc[qg][kb][j] * sl2 - mnew); sacc[qg][kb][j] = pv; ps += pv; }
;                 lsum[qg] = lsum[qg] * alpha + ps;
; #pragma unroll
;                 for (int d = 0; d < 8; ++d) oacc[qg][d] *= alpha;
;                 u32x4 w; w.x = cvt_pk_bf16(sacc[qg][0][0], sacc[qg][0][1]); w.y = cvt_pk_bf16(sacc[qg][0][2], sacc[qg][0][3]);
;                 w.z = cvt_pk_bf16(sacc[qg][1][0], sacc[qg][1][1]); w.w = cvt_pk_bf16(sacc[qg][1][2], sacc[qg][1][3]);
;                 pb[qg] = __builtin_bit_cast(bf16x8, w);
;             }
; #pragma unroll
;             for (int dh = 0; dh < 4; ++dh) {
;                 bf16x8 vfr[2];
; #pragma unroll
;                 for (int d4 = 0; d4 < 2; ++d4) {
;                     const int d = dh * 2 + d4;
;                     const u32x2 lo = *(const LAS u32x2*)(vb_ + (d * 16 + r16) * VROW + (kc * 32 + q4 * 4) * 2);
;                     const u32x2 hi = *(const LAS u32x2*)(vb_ + (d * 16 + r16) * VROW + (kc * 32 + 16 + q4 * 4) * 2);
;                     u32x4 w; w.x = lo.x; w.y = lo.y; w.z = hi.x; w.w = hi.y;
;                     vfr[d4] = __builtin_bit_cast(bf16x8, w);
;                 }
;                 __builtin_amdgcn_s_setprio(1);
; #pragma unroll
;                 for (int d4 = 0; d4 < 2; ++d4) { const int d = dh * 2 + d4; oacc[0][d] = MFMA16(vfr[d4], pb[0], oacc[0][d]); oacc[1][d] = MFMA16(vfr[d4], pb[1], oacc[1][d]); }
;                 __builtin_amdgcn_s_setprio(0);
;             }
	v_mfma_f32_16x16x32_bf16 v[112:115], v[160:163], v[16:19], v[112:115]
	v_sub_f32_e32 v193, v242, v192
	v_sub_f32_e32 v195, v243, v194
	v_exp_f32_e32 v246, v193
	v_mfma_f32_16x16x32_bf16 v[120:123], v[160:163], v[40:43], v[120:123]
	v_exp_f32_e32 v248, v195
	v_mov_b32_e32 v242, v192
	v_mov_b32_e32 v243, v194
	ds_read_b128 v[160:163], v240 offset:6656
	s_waitcnt lgkmcnt(5)
	v_mfma_f32_16x16x32_bf16 v[112:115], v[164:167], v[20:23], v[112:115]
	v_pk_fma_f32 v[128:129], v[128:129], v[254:255], v[192:193] op_sel_hi:[1,0,0] neg_lo:[0,0,1] neg_hi:[0,0,1]
	v_pk_fma_f32 v[136:137], v[136:137], v[254:255], v[194:195] op_sel_hi:[1,0,0] neg_lo:[0,0,1] neg_hi:[0,0,1]
	v_pk_fma_f32 v[130:131], v[130:131], v[254:255], v[192:193] op_sel_hi:[1,0,0] neg_lo:[0,0,1] neg_hi:[0,0,1]
	v_mfma_f32_16x16x32_bf16 v[120:123], v[164:167], v[44:47], v[120:123]
	v_pk_fma_f32 v[138:139], v[138:139], v[254:255], v[194:195] op_sel_hi:[1,0,0] neg_lo:[0,0,1] neg_hi:[0,0,1]
	v_pk_fma_f32 v[132:133], v[132:133], v[254:255], v[192:193] op_sel_hi:[1,0,0] neg_lo:[0,0,1] neg_hi:[0,0,1]
	v_pk_fma_f32 v[140:141], v[140:141], v[254:255], v[194:195] op_sel_hi:[1,0,0] neg_lo:[0,0,1] neg_hi:[0,0,1]
	ds_read_b128 v[164:167], v240 offset:6720
	s_waitcnt lgkmcnt(5)
	v_mfma_f32_16x16x32_bf16 v[116:119], v[144:147], v[0:3], 0
	v_pk_fma_f32 v[134:135], v[134:135], v[254:255], v[192:193] op_sel_hi:[1,0,0] neg_lo:[0,0,1] neg_hi:[0,0,1]
	v_pk_fma_f32 v[142:143], v[142:143], v[254:255], v[194:195] op_sel_hi:[1,0,0] neg_lo:[0,0,1] neg_hi:[0,0,1]
	v_exp_f32_e32 v128, v128
	v_mfma_f32_16x16x32_bf16 v[124:127], v[144:147], v[24:27], 0
	v_exp_f32_e32 v136, v136
	v_exp_f32_e32 v129, v129
	v_exp_f32_e32 v137, v137
	ds_read_b64 v[168:169], v241 offset:64
	ds_read_b64 v[170:171], v241 offset:96
	s_waitcnt lgkmcnt(6)
	v_mfma_f32_16x16x32_bf16 v[116:119], v[148:151], v[4:7], v[116:119]
	v_exp_f32_e32 v130, v130
	v_exp_f32_e32 v138, v138
	v_exp_f32_e32 v131, v131
	v_mfma_f32_16x16x32_bf16 v[124:127], v[148:151], v[28:31], v[124:127]
	v_exp_f32_e32 v139, v139
	v_exp_f32_e32 v132, v132
	v_exp_f32_e32 v140, v140
	ds_read_b64 v[172:173], v241 offset:2368
	ds_read_b64 v[174:175], v241 offset:2400
	s_waitcnt lgkmcnt(7)
	v_mfma_f32_16x16x32_bf16 v[116:119], v[152:155], v[8:11], v[116:119]
	v_exp_f32_e32 v133, v133
	v_exp_f32_e32 v141, v141
	v_exp_f32_e32 v134, v134
	v_mfma_f32_16x16x32_bf16 v[124:127], v[152:155], v[32:35], v[124:127]
	v_exp_f32_e32 v142, v142
	v_exp_f32_e32 v135, v135
	v_exp_f32_e32 v143, v143
	ds_read_b64 v[176:177], v241 offset:4672
	ds_read_b64 v[178:179], v241 offset:4704
	s_waitcnt lgkmcnt(8)
	v_mfma_f32_16x16x32_bf16 v[116:119], v[156:159], v[12:15], v[116:119]
	v_pk_add_f32 v[196:197], v[128:129], v[130:131]
	v_pk_add_f32 v[198:199], v[136:137], v[138:139]
	v_pk_add_f32 v[196:197], v[196:197], v[132:133]
	v_mfma_f32_16x16x32_bf16 v[124:127], v[156:159], v[36:39], v[124:127]
	v_pk_add_f32 v[198:199], v[198:199], v[140:141]
	v_pk_add_f32 v[196:197], v[196:197], v[134:135]
	v_pk_add_f32 v[198:199], v[198:199], v[142:143]
	ds_read_b64 v[180:181], v241 offset:6976
	ds_read_b64 v[182:183], v241 offset:7008
	s_waitcnt lgkmcnt(9)
	v_mfma_f32_16x16x32_bf16 v[116:119], v[160:163], v[16:19], v[116:119]
	v_add_f32_e32 v193, v196, v197
	v_add_f32_e32 v195, v198, v199
	v_fma_f32 v244, v244, v246, v193
	v_mfma_f32_16x16x32_bf16 v[124:127], v[160:163], v[40:43], v[124:127]
	v_fma_f32 v245, v245, v248, v195
	v_cvt_pk_bf16_f32 v184, v128, v129
	v_cvt_pk_bf16_f32 v188, v136, v137
	s_waitcnt lgkmcnt(8)
	v_mfma_f32_16x16x32_bf16 v[116:119], v[164:167], v[20:23], v[116:119]
	v_cvt_pk_bf16_f32 v185, v130, v131
	v_cvt_pk_bf16_f32 v189, v138, v139
	v_cvt_pk_bf16_f32 v186, v132, v133
	v_mfma_f32_16x16x32_bf16 v[124:127], v[164:167], v[44:47], v[124:127]
	v_cvt_pk_bf16_f32 v190, v140, v141
	v_cvt_pk_bf16_f32 v187, v134, v135
	v_cvt_pk_bf16_f32 v191, v142, v143
	s_or_b64 vcc, s[68:69], s[0:1]
	s_cbranch_vccz dn1_nr2
	v_pk_mul_f32 v[48:49], v[48:49], v[246:247] op_sel_hi:[1,0]
	v_pk_mul_f32 v[50:51], v[50:51], v[246:247] op_sel_hi:[1,0]
	v_pk_mul_f32 v[80:81], v[80:81], v[248:249] op_sel_hi:[1,0]
	v_pk_mul_f32 v[82:83], v[82:83], v[248:249] op_sel_hi:[1,0]
	s_waitcnt lgkmcnt(6)
	v_mfma_f32_16x16x32_bf16 v[48:51], v[168:171], v[184:187], v[48:51]
	v_pk_mul_f32 v[52:53], v[52:53], v[246:247] op_sel_hi:[1,0]
	v_pk_mul_f32 v[54:55], v[54:55], v[246:247] op_sel_hi:[1,0]
	v_mfma_f32_16x16x32_bf16 v[80:83], v[168:171], v[188:191], v[80:83]
	v_pk_mul_f32 v[84:85], v[84:85], v[248:249] op_sel_hi:[1,0]
	v_pk_mul_f32 v[86:87], v[86:87], v[248:249] op_sel_hi:[1,0]
	ds_read_b64 v[168:169], v241 offset:9280
	ds_read_b64 v[170:171], v241 offset:9312
	s_waitcnt lgkmcnt(6)
	v_mfma_f32_16x16x32_bf16 v[52:55], v[172:175], v[184:187], v[52:55]
	v_pk_mul_f32 v[56:57], v[56:57], v[246:247] op_sel_hi:[1,0]
	v_pk_mul_f32 v[58:59], v[58:59], v[246:247] op_sel_hi:[1,0]
	v_mfma_f32_16x16x32_bf16 v[84:87], v[172:175], v[188:191], v[84:87]
	v_pk_mul_f32 v[88:89], v[88:89], v[248:249] op_sel_hi:[1,0]
	v_pk_mul_f32 v[90:91], v[90:91], v[248:249] op_sel_hi:[1,0]
	ds_read_b64 v[172:173], v241 offset:11584
	ds_read_b64 v[174:175], v241 offset:11616
	s_waitcnt lgkmcnt(6)
	v_mfma_f32_16x16x32_bf16 v[56:59], v[176:179], v[184:187], v[56:59]
	v_pk_mul_f32 v[60:61], v[60:61], v[246:247] op_sel_hi:[1,0]
	v_pk_mul_f32 v[62:63], v[62:63], v[246:247] op_sel_hi:[1,0]
	v_mfma_f32_16x16x32_bf16 v[88:91], v[176:179], v[188:191], v[88:91]
	v_pk_mul_f32 v[92:93], v[92:93], v[248:249] op_sel_hi:[1,0]
	v_pk_mul_f32 v[94:95], v[94:95], v[248:249] op_sel_hi:[1,0]
	ds_read_b64 v[176:177], v241 offset:13888
	ds_read_b64 v[178:179], v241 offset:13920
	s_waitcnt lgkmcnt(6)
; #define LAS __attribute__((address_space(3)))
; #define MFMA16(a, b, c) __builtin_amdgcn_mfma_f32_16x16x32_bf16((a), (b), (c), 0, 0, 0)
; template <int DK>
; DI void dense_attn_item(LAS unsigned char* lds, const bf16_t* Qb, int ldq, const bf16_t* Kb, int ldk, const bf16_t* Kpe, const bf16_t* Vt, int nkeys, float sl2, bf16_t* Ob) {
;     ...
; #pragma unroll
;             for (int dh = 0; dh < 4; ++dh) {
;                 bf16x8 vfr[2];
; #pragma unroll
;                 for (int d4 = 0; d4 < 2; ++d4) {
;                     const int d = dh * 2 + d4;
;                     const u32x2 lo = *(const LAS u32x2*)(vb_ + (d * 16 + r16) * VROW + (kc * 32 + q4 * 4) * 2);
;                     const u32x2 hi = *(const LAS u32x2*)(vb_ + (d * 16 + r16) * VROW + (kc * 32 + 16 + q4 * 4) * 2);
;                     u32x4 w; w.x = lo.x; w.y = lo.y; w.z = hi.x; w.w = hi.y;
;                     vfr[d4] = __builtin_bit_cast(bf16x8, w);
;                 }
;                 __builtin_amdgcn_s_setprio(1);
; #pragma unroll
;                 for (int d4 = 0; d4 < 2; ++d4) { const int d = dh * 2 + d4; oacc[0][d] = MFMA16(vfr[d4], pb[0], oacc[0][d]); oacc[1][d] = MFMA16(vfr[d4], pb[1], oacc[1][d]); }
;                 __builtin_amdgcn_s_setprio(0);
;             }
	v_mfma_f32_16x16x32_bf16 v[60:63], v[180:183], v[184:187], v[60:63]
	v_pk_mul_f32 v[64:65], v[64:65], v[246:247] op_sel_hi:[1,0]
	v_pk_mul_f32 v[66:67], v[66:67], v[246:247] op_sel_hi:[1,0]
	v_mfma_f32_16x16x32_bf16 v[92:95], v[180:183], v[188:191], v[92:95]
	v_pk_mul_f32 v[96:97], v[96:97], v[248:249] op_sel_hi:[1,0]
	v_pk_mul_f32 v[98:99], v[98:99], v[248:249] op_sel_hi:[1,0]
	ds_read_b64 v[180:181], v241 offset:16192
	ds_read_b64 v[182:183], v241 offset:16224
	s_waitcnt lgkmcnt(6)
	v_mfma_f32_16x16x32_bf16 v[64:67], v[168:171], v[184:187], v[64:67]
	v_pk_mul_f32 v[68:69], v[68:69], v[246:247] op_sel_hi:[1,0]
	v_pk_mul_f32 v[70:71], v[70:71], v[246:247] op_sel_hi:[1,0]
	v_mfma_f32_16x16x32_bf16 v[96:99], v[168:171], v[188:191], v[96:99]
	v_pk_mul_f32 v[100:101], v[100:101], v[248:249] op_sel_hi:[1,0]
	v_pk_mul_f32 v[102:103], v[102:103], v[248:249] op_sel_hi:[1,0]
	s_waitcnt lgkmcnt(4)
	v_mfma_f32_16x16x32_bf16 v[68:71], v[172:175], v[184:187], v[68:71]
	v_pk_mul_f32 v[72:73], v[72:73], v[246:247] op_sel_hi:[1,0]
	v_pk_mul_f32 v[74:75], v[74:75], v[246:247] op_sel_hi:[1,0]
	v_mfma_f32_16x16x32_bf16 v[100:103], v[172:175], v[188:191], v[100:103]
	v_pk_mul_f32 v[104:105], v[104:105], v[248:249] op_sel_hi:[1,0]
	v_pk_mul_f32 v[106:107], v[106:107], v[248:249] op_sel_hi:[1,0]
	s_waitcnt lgkmcnt(2)
	v_mfma_f32_16x16x32_bf16 v[72:75], v[176:179], v[184:187], v[72:75]
	v_pk_mul_f32 v[76:77], v[76:77], v[246:247] op_sel_hi:[1,0]
	v_pk_mul_f32 v[78:79], v[78:79], v[246:247] op_sel_hi:[1,0]
	v_mfma_f32_16x16x32_bf16 v[104:107], v[176:179], v[188:191], v[104:107]
	v_pk_mul_f32 v[108:109], v[108:109], v[248:249] op_sel_hi:[1,0]
	v_pk_mul_f32 v[110:111], v[110:111], v[248:249] op_sel_hi:[1,0]
	s_waitcnt lgkmcnt(0)
	v_mfma_f32_16x16x32_bf16 v[76:79], v[180:183], v[184:187], v[76:79]
	v_mfma_f32_16x16x32_bf16 v[108:111], v[180:183], v[188:191], v[108:111]
	s_branch dn1_jn2
dn1_nr2:
	s_nop 1
	s_waitcnt lgkmcnt(6)
	v_mfma_f32_16x16x32_bf16 v[48:51], v[168:171], v[184:187], v[48:51]
	v_mfma_f32_16x16x32_bf16 v[80:83], v[168:171], v[188:191], v[80:83]
	ds_read_b64 v[168:169], v241 offset:9280
	ds_read_b64 v[170:171], v241 offset:9312
	s_waitcnt lgkmcnt(6)
	v_mfma_f32_16x16x32_bf16 v[52:55], v[172:175], v[184:187], v[52:55]
	v_mfma_f32_16x16x32_bf16 v[84:87], v[172:175], v[188:191], v[84:87]
	ds_read_b64 v[172:173], v241 offset:11584
	ds_read_b64 v[174:175], v241 offset:11616
	s_waitcnt lgkmcnt(6)
	v_mfma_f32_16x16x32_bf16 v[56:59], v[176:179], v[184:187], v[56:59]
	v_mfma_f32_16x16x32_bf16 v[88:91], v[176:179], v[188:191], v[88:91]
	ds_read_b64 v[176:177], v241 offset:13888
	ds_read_b64 v[178:179], v241 offset:13920
	s_waitcnt lgkmcnt(6)
	v_mfma_f32_16x16x32_bf16 v[60:63], v[180:183], v[184:187], v[60:63]
	v_mfma_f32_16x16x32_bf16 v[92:95], v[180:183], v[188:191], v[92:95]
	ds_read_b64 v[180:181], v241 offset:16192
	ds_read_b64 v[182:183], v241 offset:16224
	s_waitcnt lgkmcnt(6)
	v_mfma_f32_16x16x32_bf16 v[64:67], v[168:171], v[184:187], v[64:67]
	v_mfma_f32_16x16x32_bf16 v[96:99], v[168:171], v[188:191], v[96:99]
	s_waitcnt lgkmcnt(4)
	v_mfma_f32_16x16x32_bf16 v[68:71], v[172:175], v[184:187], v[68:71]
	v_mfma_f32_16x16x32_bf16 v[100:103], v[172:175], v[188:191], v[100:103]
	s_waitcnt lgkmcnt(2)
	v_mfma_f32_16x16x32_bf16 v[72:75], v[176:179], v[184:187], v[72:75]
	v_mfma_f32_16x16x32_bf16 v[104:107], v[176:179], v[188:191], v[104:107]
	s_waitcnt lgkmcnt(0)
	v_mfma_f32_16x16x32_bf16 v[76:79], v[180:183], v[184:187], v[76:79]
	v_mfma_f32_16x16x32_bf16 v[108:111], v[180:183], v[188:191], v[108:111]
; #define LAS __attribute__((address_space(3)))
; DI unsigned xb_add(unsigned* p, unsigned v) { return __hip_atomic_fetch_add(p, v, __ATOMIC_RELAXED, __HIP_MEMORY_SCOPE_AGENT); }
; DI void st_bf16x4(bf16_t* p, f32x4 v) { u32x2 w; w.x = cvt_pk_bf16(v[0], v[1]); w.y = cvt_pk_bf16(v[2], v[3]); *(u32x2*)p = w; }
; DI int next_item(unsigned* ctr, volatile LAS int* slot) {
;     __syncthreads();
;     if (threadIdx.x == 0) *slot = (int)xb_add(ctr, 1u);
;     __syncthreads();
; template <int DK>
; DI void dense_attn_item(LAS unsigned char* lds, const bf16_t* Qb, int ldq, const bf16_t* Kb, int ldk, const bf16_t* Kpe, const bf16_t* Vt, int nkeys, float sl2, bf16_t* Ob) {
;     ...
;         if (kt + 1 < ntiles) DA_STORE(cur ^ 1);
;         __syncthreads();
;     }
; #pragma unroll
;     for (int qg = 0; qg < 2; ++qg) {
;         float l = lsum[qg]; l += __shfl_xor(l, 16); l += __shfl_xor(l, 32);
;         const float inv = 1.f / l;
;         bf16_t* op = Ob + (size_t)(wid * 32 + qg * 16 + r16) * DM + q4 * 4;
; #pragma unroll
;         for (int d = 0; d < 8; ++d) st_bf16x4(op + d * 16, oacc[qg][d] * inv);
;     }
dn1_jn2:
	s_mov_b32 s27, s57
	s_add_u32 s23, s23, 1
	s_cmp_lt_u32 s23, 36
	s_cbranch_scc1 dn1_top
	s_waitcnt vmcnt(0) lgkmcnt(0)
	v_mov_b32_e32 v192, v244
	v_mov_b32_e32 v193, v244
	v_mov_b32_e32 v194, v245
	v_mov_b32_e32 v195, v245
	s_nop 1
	v_permlane16_swap_b32_e32 v192, v193
	v_permlane16_swap_b32_e32 v194, v195
	v_add_f32_e32 v192, v192, v193
	v_add_f32_e32 v194, v194, v195
	v_mov_b32_e32 v193, v192
	v_mov_b32_e32 v195, v194
	s_nop 1
	v_permlane32_swap_b32_e32 v192, v193
	v_permlane32_swap_b32_e32 v194, v195
	v_add_f32_e32 v192, v192, v193
	v_add_f32_e32 v194, v194, v195
	v_rcp_f32_e32 v193, v192
	v_rcp_f32_e32 v195, v194
	s_nop 0
	v_fma_f32 v192, -v192, v193, 1.0
	v_fma_f32 v194, -v194, v195, 1.0
	v_fma_f32 v246, v192, v193, v193
	v_fma_f32 v248, v194, v195, v195
	v_pk_mul_f32 v[48:49], v[48:49], v[246:247] op_sel_hi:[1,0]
	v_pk_mul_f32 v[50:51], v[50:51], v[246:247] op_sel_hi:[1,0]
	v_cvt_pk_bf16_f32 v48, v48, v49
	v_cvt_pk_bf16_f32 v49, v50, v51
	global_store_dwordx2 v250, v[48:49], s[20:21] offset:0
	v_pk_mul_f32 v[52:53], v[52:53], v[246:247] op_sel_hi:[1,0]
	v_pk_mul_f32 v[54:55], v[54:55], v[246:247] op_sel_hi:[1,0]
	v_cvt_pk_bf16_f32 v52, v52, v53
	v_cvt_pk_bf16_f32 v53, v54, v55
	global_store_dwordx2 v250, v[52:53], s[20:21] offset:32
	v_pk_mul_f32 v[56:57], v[56:57], v[246:247] op_sel_hi:[1,0]
	v_pk_mul_f32 v[58:59], v[58:59], v[246:247] op_sel_hi:[1,0]
	v_cvt_pk_bf16_f32 v56, v56, v57
	v_cvt_pk_bf16_f32 v57, v58, v59
	global_store_dwordx2 v250, v[56:57], s[20:21] offset:64
	v_pk_mul_f32 v[60:61], v[60:61], v[246:247] op_sel_hi:[1,0]
	v_pk_mul_f32 v[62:63], v[62:63], v[246:247] op_sel_hi:[1,0]
	v_cvt_pk_bf16_f32 v60, v60, v61
	v_cvt_pk_bf16_f32 v61, v62, v63
	global_store_dwordx2 v250, v[60:61], s[20:21] offset:96
	v_pk_mul_f32 v[64:65], v[64:65], v[246:247] op_sel_hi:[1,0]
	v_pk_mul_f32 v[66:67], v[66:67], v[246:247] op_sel_hi:[1,0]
	v_cvt_pk_bf16_f32 v64, v64, v65
	v_cvt_pk_bf16_f32 v65, v66, v67
	global_store_dwordx2 v250, v[64:65], s[20:21] offset:128
	v_pk_mul_f32 v[68:69], v[68:69], v[246:247] op_sel_hi:[1,0]
	v_pk_mul_f32 v[70:71], v[70:71], v[246:247] op_sel_hi:[1,0]
	v_cvt_pk_bf16_f32 v68, v68, v69
	v_cvt_pk_bf16_f32 v69, v70, v71
	global_store_dwordx2 v250, v[68:69], s[20:21] offset:160
	v_pk_mul_f32 v[72:73], v[72:73], v[246:247] op_sel_hi:[1,0]
	v_pk_mul_f32 v[74:75], v[74:75], v[246:247] op_sel_hi:[1,0]
	v_cvt_pk_bf16_f32 v72, v72, v73
	v_cvt_pk_bf16_f32 v73, v74, v75
	global_store_dwordx2 v250, v[72:73], s[20:21] offset:192
	v_pk_mul_f32 v[76:77], v[76:77], v[246:247] op_sel_hi:[1,0]
	v_pk_mul_f32 v[78:79], v[78:79], v[246:247] op_sel_hi:[1,0]
	v_cvt_pk_bf16_f32 v76, v76, v77
	v_cvt_pk_bf16_f32 v77, v78, v79
	global_store_dwordx2 v250, v[76:77], s[20:21] offset:224
	v_pk_mul_f32 v[80:81], v[80:81], v[248:249] op_sel_hi:[1,0]
	v_pk_mul_f32 v[82:83], v[82:83], v[248:249] op_sel_hi:[1,0]
	v_cvt_pk_bf16_f32 v80, v80, v81
	v_cvt_pk_bf16_f32 v81, v82, v83
	global_store_dwordx2 v251, v[80:81], s[20:21] offset:0
	v_pk_mul_f32 v[84:85], v[84:85], v[248:249] op_sel_hi:[1,0]
	v_pk_mul_f32 v[86:87], v[86:87], v[248:249] op_sel_hi:[1,0]
	v_cvt_pk_bf16_f32 v84, v84, v85
	v_cvt_pk_bf16_f32 v85, v86, v87
	global_store_dwordx2 v251, v[84:85], s[20:21] offset:32
	v_pk_mul_f32 v[88:89], v[88:89], v[248:249] op_sel_hi:[1,0]
	v_pk_mul_f32 v[90:91], v[90:91], v[248:249] op_sel_hi:[1,0]
	v_cvt_pk_bf16_f32 v88, v88, v89
	v_cvt_pk_bf16_f32 v89, v90, v91
	global_store_dwordx2 v251, v[88:89], s[20:21] offset:64
	v_pk_mul_f32 v[92:93], v[92:93], v[248:249] op_sel_hi:[1,0]
	v_pk_mul_f32 v[94:95], v[94:95], v[248:249] op_sel_hi:[1,0]
	v_cvt_pk_bf16_f32 v92, v92, v93
	v_cvt_pk_bf16_f32 v93, v94, v95
	global_store_dwordx2 v251, v[92:93], s[20:21] offset:96
	v_pk_mul_f32 v[96:97], v[96:97], v[248:249] op_sel_hi:[1,0]
	v_pk_mul_f32 v[98:99], v[98:99], v[248:249] op_sel_hi:[1,0]
	v_cvt_pk_bf16_f32 v96, v96, v97
	v_cvt_pk_bf16_f32 v97, v98, v99
	global_store_dwordx2 v251, v[96:97], s[20:21] offset:128
	v_pk_mul_f32 v[100:101], v[100:101], v[248:249] op_sel_hi:[1,0]
	v_pk_mul_f32 v[102:103], v[102:103], v[248:249] op_sel_hi:[1,0]
	v_cvt_pk_bf16_f32 v100, v100, v101
	v_cvt_pk_bf16_f32 v101, v102, v103
	global_store_dwordx2 v251, v[100:101], s[20:21] offset:160
	v_pk_mul_f32 v[104:105], v[104:105], v[248:249] op_sel_hi:[1,0]
	v_pk_mul_f32 v[106:107], v[106:107], v[248:249] op_sel_hi:[1,0]
	v_cvt_pk_bf16_f32 v104, v104, v105
	v_cvt_pk_bf16_f32 v105, v106, v107
	global_store_dwordx2 v251, v[104:105], s[20:21] offset:192
	v_pk_mul_f32 v[108:109], v[108:109], v[248:249] op_sel_hi:[1,0]
	v_pk_mul_f32 v[110:111], v[110:111], v[248:249] op_sel_hi:[1,0]
	v_cvt_pk_bf16_f32 v108, v108, v109
	v_cvt_pk_bf16_f32 v109, v110, v111
	global_store_dwordx2 v251, v[108:109], s[20:21] offset:224
	v_mov_b32_e32 v133, 0
	s_waitcnt vmcnt(0)
	s_barrier
	s_and_saveexec_b64 s[0:1], s[24:25]
	s_cbranch_execz .LBB0_2592
	s_mov_b64 s[4:5], exec
	v_mbcnt_lo_u32_b32 v0, s4, 0
	v_mbcnt_hi_u32_b32 v0, s5, v0
	v_cmp_eq_u32_e32 vcc, 0, v0
	s_and_saveexec_b64 s[2:3], vcc
	s_cbranch_execz .LBB0_2591
	s_bcnt1_i32_b64 s4, s[4:5]
	v_mov_b32_e32 v1, s4
	global_atomic_add v1, v133, v1, s[34:35] sc0
	s_branch .LBB0_2591
